# v108 plus one static s_setprio 1 for waves 4-7 before each GEMM K-loop (the documented recipe: static raise for the younger half, no per-phase flips)
# speedup vs baseline: 1.0087x; 1.0087x over previous
.Lprio_y0:
.LBB0_197:
	ds_read_b128 v[144:147], v151
	ds_read_b128 v[154:157], v151 offset:1024
	ds_read_b128 v[158:161], v151 offset:2048
	ds_read_b128 v[162:165], v151 offset:3072
	s_add_u32 s18, s16, 0xfff80080
	s_addc_u32 s19, s17, -1
	s_cmp_eq_u32 s78, 28
	s_cselect_b32 s21, s5, s19
	s_cselect_b32 s20, s9, s18
	s_cselect_b32 s19, s7, s77
	s_cselect_b32 s18, s15, s76
	s_add_i32 m0, s24, 0xc000
	ds_read_b128 v[166:169], v152
	ds_read_b128 v[170:173], v152 offset:1024
	ds_read_b128 v[174:177], v152 offset:2048
	ds_read_b128 v[178:181], v152 offset:3072
	ds_read_b128 v[182:185], v152 offset:4096
	ds_read_b128 v[186:189], v152 offset:5120
	ds_read_b128 v[190:193], v152 offset:6144
	ds_read_b128 v[194:197], v152 offset:7168
	global_load_lds_dwordx4 v136, s[16:17]
	s_add_i32 m0, s24, 0xe000
	s_nop 0
	global_load_lds_dwordx4 v138, s[16:17]
	s_waitcnt lgkmcnt(8)
	s_barrier
	s_waitcnt lgkmcnt(0)
	v_mfma_f32_16x16x32_f16 v[124:127], v[144:147], v[166:169], v[124:127]
	v_mfma_f32_16x16x32_f16 v[120:123], v[158:161], v[166:169], v[120:123]
	v_mfma_f32_16x16x32_f16 v[108:111], v[144:147], v[174:177], v[108:111]
	v_mfma_f32_16x16x32_f16 v[104:107], v[158:161], v[174:177], v[104:107]
	v_mfma_f32_16x16x32_f16 v[92:95], v[144:147], v[182:185], v[92:95]
	v_mfma_f32_16x16x32_f16 v[88:91], v[158:161], v[182:185], v[88:91]
	v_mfma_f32_16x16x32_f16 v[76:79], v[144:147], v[190:193], v[76:79]
	v_mfma_f32_16x16x32_f16 v[72:75], v[158:161], v[190:193], v[72:75]
	v_mfma_f32_16x16x32_f16 v[124:127], v[154:157], v[170:173], v[124:127]
	v_mfma_f32_16x16x32_f16 v[120:123], v[162:165], v[170:173], v[120:123]
	v_mfma_f32_16x16x32_f16 v[108:111], v[154:157], v[178:181], v[108:111]
	v_mfma_f32_16x16x32_f16 v[104:107], v[162:165], v[178:181], v[104:107]
	v_mfma_f32_16x16x32_f16 v[92:95], v[154:157], v[186:189], v[92:95]
	v_mfma_f32_16x16x32_f16 v[88:91], v[162:165], v[186:189], v[88:91]
	v_mfma_f32_16x16x32_f16 v[76:79], v[154:157], v[194:197], v[76:79]
	v_mfma_f32_16x16x32_f16 v[72:75], v[162:165], v[194:197], v[72:75]
	s_barrier
	s_add_i32 s79, s68, s23
	s_add_u32 s72, s18, s0
	s_addc_u32 s73, s19, s1
	s_mov_b32 m0, s79
	ds_read_b128 v[198:201], v153
	ds_read_b128 v[202:205], v153 offset:1024
	ds_read_b128 v[206:209], v153 offset:2048
	ds_read_b128 v[210:213], v153 offset:3072
	global_load_lds_dwordx4 v130, s[18:19]
	s_add_i32 m0, s79, 0x2000
	s_nop 0
	global_load_lds_dwordx4 v134, s[18:19]
	s_barrier
	s_waitcnt lgkmcnt(0)
	v_mfma_f32_16x16x32_f16 v[116:119], v[198:201], v[166:169], v[116:119]
	v_mfma_f32_16x16x32_f16 v[112:115], v[206:209], v[166:169], v[112:115]
	v_mfma_f32_16x16x32_f16 v[100:103], v[198:201], v[174:177], v[100:103]
	v_mfma_f32_16x16x32_f16 v[96:99], v[206:209], v[174:177], v[96:99]
	v_mfma_f32_16x16x32_f16 v[84:87], v[198:201], v[182:185], v[84:87]
	v_mfma_f32_16x16x32_f16 v[80:83], v[206:209], v[182:185], v[80:83]
	v_mfma_f32_16x16x32_f16 v[68:71], v[198:201], v[190:193], v[68:71]
	v_mfma_f32_16x16x32_f16 v[64:67], v[206:209], v[190:193], v[64:67]
	v_mfma_f32_16x16x32_f16 v[116:119], v[202:205], v[170:173], v[116:119]
	v_mfma_f32_16x16x32_f16 v[112:115], v[210:213], v[170:173], v[112:115]
	v_mfma_f32_16x16x32_f16 v[100:103], v[202:205], v[178:181], v[100:103]
	v_mfma_f32_16x16x32_f16 v[96:99], v[210:213], v[178:181], v[96:99]
	v_mfma_f32_16x16x32_f16 v[84:87], v[202:205], v[186:189], v[84:87]
	v_mfma_f32_16x16x32_f16 v[80:83], v[210:213], v[186:189], v[80:83]
	v_mfma_f32_16x16x32_f16 v[68:71], v[202:205], v[194:197], v[68:71]
	v_mfma_f32_16x16x32_f16 v[64:67], v[210:213], v[194:197], v[64:67]
	s_barrier
	s_mov_b32 m0, s24
	s_add_u32 s74, s20, s0
	s_addc_u32 s75, s21, s1
	ds_read_b128 v[166:169], v152 offset:16384
	ds_read_b128 v[170:173], v152 offset:17408
	ds_read_b128 v[174:177], v152 offset:18432
	ds_read_b128 v[178:181], v152 offset:19456
	ds_read_b128 v[182:185], v152 offset:20480
	ds_read_b128 v[186:189], v152 offset:21504
	ds_read_b128 v[190:193], v152 offset:22528
	ds_read_b128 v[194:197], v152 offset:23552
	global_load_lds_dwordx4 v128, s[20:21]
	s_mov_b32 m0, s25
	s_nop 0
	global_load_lds_dwordx4 v132, s[20:21]
	s_barrier
	s_waitcnt lgkmcnt(0)
	v_mfma_f32_16x16x32_f16 v[60:63], v[144:147], v[166:169], v[60:63]
	v_mfma_f32_16x16x32_f16 v[56:59], v[158:161], v[166:169], v[56:59]
	v_mfma_f32_16x16x32_f16 v[44:47], v[144:147], v[174:177], v[44:47]
	v_mfma_f32_16x16x32_f16 v[40:43], v[158:161], v[174:177], v[40:43]
	v_mfma_f32_16x16x32_f16 v[28:31], v[144:147], v[182:185], v[28:31]
	v_mfma_f32_16x16x32_f16 v[24:27], v[158:161], v[182:185], v[24:27]
	v_mfma_f32_16x16x32_f16 v[12:15], v[144:147], v[190:193], v[12:15]
	v_mfma_f32_16x16x32_f16 v[8:11], v[158:161], v[190:193], v[8:11]
	v_mfma_f32_16x16x32_f16 v[60:63], v[154:157], v[170:173], v[60:63]
	v_mfma_f32_16x16x32_f16 v[56:59], v[162:165], v[170:173], v[56:59]
	v_mfma_f32_16x16x32_f16 v[44:47], v[154:157], v[178:181], v[44:47]
	v_mfma_f32_16x16x32_f16 v[40:43], v[162:165], v[178:181], v[40:43]
	v_mfma_f32_16x16x32_f16 v[28:31], v[154:157], v[186:189], v[28:31]
	v_mfma_f32_16x16x32_f16 v[24:27], v[162:165], v[186:189], v[24:27]
	v_mfma_f32_16x16x32_f16 v[12:15], v[154:157], v[194:197], v[12:15]
	v_mfma_f32_16x16x32_f16 v[8:11], v[162:165], v[194:197], v[8:11]
	s_barrier
	s_add_u32 s80, s18, 0x80000
	s_addc_u32 s81, s19, 0
	s_add_i32 s79, s69, s23
	s_mov_b32 m0, s79
	s_nop 0
	global_load_lds_dwordx4 v130, s[80:81]
	s_add_i32 m0, s79, 0x2000
	s_nop 0
	global_load_lds_dwordx4 v134, s[80:81]
	s_waitcnt vmcnt(6)
	s_barrier
	v_mfma_f32_16x16x32_f16 v[52:55], v[198:201], v[166:169], v[52:55]
	v_mfma_f32_16x16x32_f16 v[48:51], v[206:209], v[166:169], v[48:51]
	v_mfma_f32_16x16x32_f16 v[36:39], v[198:201], v[174:177], v[36:39]
	v_mfma_f32_16x16x32_f16 v[32:35], v[206:209], v[174:177], v[32:35]
	v_mfma_f32_16x16x32_f16 v[20:23], v[198:201], v[182:185], v[20:23]
	v_mfma_f32_16x16x32_f16 v[16:19], v[206:209], v[182:185], v[16:19]
	v_mfma_f32_16x16x32_f16 v[4:7], v[198:201], v[190:193], v[4:7]
	v_mfma_f32_16x16x32_f16 v[0:3], v[206:209], v[190:193], v[0:3]
	v_mfma_f32_16x16x32_f16 v[52:55], v[202:205], v[170:173], v[52:55]
	v_mfma_f32_16x16x32_f16 v[48:51], v[210:213], v[170:173], v[48:51]
	v_mfma_f32_16x16x32_f16 v[36:39], v[202:205], v[178:181], v[36:39]
	v_mfma_f32_16x16x32_f16 v[32:35], v[210:213], v[178:181], v[32:35]
	v_mfma_f32_16x16x32_f16 v[20:23], v[202:205], v[186:189], v[20:23]
	v_mfma_f32_16x16x32_f16 v[16:19], v[210:213], v[186:189], v[16:19]
	v_mfma_f32_16x16x32_f16 v[4:7], v[202:205], v[194:197], v[4:7]
	v_mfma_f32_16x16x32_f16 v[0:3], v[210:213], v[194:197], v[0:3]
	s_barrier
	s_add_i32 s79, 0, 0x18000
	v_add_u32_e32 v162, s79, v149
	ds_read_b128 v[144:147], v162
	ds_read_b128 v[154:157], v162 offset:1024
	ds_read_b128 v[158:161], v162 offset:2048
	ds_read_b128 v[162:165], v162 offset:3072
	s_add_u32 s20, s20, 0x80000
	s_addc_u32 s21, s21, 0
	s_mov_b32 m0, s26
	ds_read_b128 v[166:169], v152 offset:32768
	ds_read_b128 v[170:173], v152 offset:33792
	ds_read_b128 v[174:177], v152 offset:34816
	ds_read_b128 v[178:181], v152 offset:35840
	ds_read_b128 v[182:185], v152 offset:36864
	ds_read_b128 v[186:189], v152 offset:37888
	ds_read_b128 v[190:193], v152 offset:38912
	ds_read_b128 v[194:197], v152 offset:39936
	global_load_lds_dwordx4 v128, s[20:21]
	s_mov_b32 m0, s27
	s_nop 0
	global_load_lds_dwordx4 v132, s[20:21]
	s_waitcnt lgkmcnt(8)
	s_barrier
	s_waitcnt lgkmcnt(0)
	v_mfma_f32_16x16x32_f16 v[124:127], v[144:147], v[166:169], v[124:127]
	v_mfma_f32_16x16x32_f16 v[120:123], v[158:161], v[166:169], v[120:123]
	v_mfma_f32_16x16x32_f16 v[108:111], v[144:147], v[174:177], v[108:111]
	v_mfma_f32_16x16x32_f16 v[104:107], v[158:161], v[174:177], v[104:107]
	v_mfma_f32_16x16x32_f16 v[92:95], v[144:147], v[182:185], v[92:95]
	v_mfma_f32_16x16x32_f16 v[88:91], v[158:161], v[182:185], v[88:91]
	v_mfma_f32_16x16x32_f16 v[76:79], v[144:147], v[190:193], v[76:79]
	v_mfma_f32_16x16x32_f16 v[72:75], v[158:161], v[190:193], v[72:75]
	v_mfma_f32_16x16x32_f16 v[124:127], v[154:157], v[170:173], v[124:127]
	v_mfma_f32_16x16x32_f16 v[120:123], v[162:165], v[170:173], v[120:123]
	v_mfma_f32_16x16x32_f16 v[108:111], v[154:157], v[178:181], v[108:111]
	v_mfma_f32_16x16x32_f16 v[104:107], v[162:165], v[178:181], v[104:107]
	v_mfma_f32_16x16x32_f16 v[92:95], v[154:157], v[186:189], v[92:95]
	v_mfma_f32_16x16x32_f16 v[88:91], v[162:165], v[186:189], v[88:91]
	v_mfma_f32_16x16x32_f16 v[76:79], v[154:157], v[194:197], v[76:79]
	v_mfma_f32_16x16x32_f16 v[72:75], v[162:165], v[194:197], v[72:75]
	s_barrier
	s_add_i32 s20, 0, 0x1c000
	s_add_i32 s21, s79, s23
	v_add_u32_e32 v210, s20, v149
	s_mov_b32 m0, s21
	ds_read_b128 v[198:201], v210
	ds_read_b128 v[202:205], v210 offset:1024
	ds_read_b128 v[206:209], v210 offset:2048
	ds_read_b128 v[210:213], v210 offset:3072
	global_load_lds_dwordx4 v130, s[72:73]
	s_add_i32 m0, s21, 0x2000
	s_nop 0
	global_load_lds_dwordx4 v134, s[72:73]
	s_barrier
	s_waitcnt lgkmcnt(0)
	v_mfma_f32_16x16x32_f16 v[116:119], v[198:201], v[166:169], v[116:119]
	v_mfma_f32_16x16x32_f16 v[112:115], v[206:209], v[166:169], v[112:115]
	v_mfma_f32_16x16x32_f16 v[100:103], v[198:201], v[174:177], v[100:103]
	v_mfma_f32_16x16x32_f16 v[96:99], v[206:209], v[174:177], v[96:99]
	v_mfma_f32_16x16x32_f16 v[84:87], v[198:201], v[182:185], v[84:87]
	v_mfma_f32_16x16x32_f16 v[80:83], v[206:209], v[182:185], v[80:83]
	v_mfma_f32_16x16x32_f16 v[68:71], v[198:201], v[190:193], v[68:71]
	v_mfma_f32_16x16x32_f16 v[64:67], v[206:209], v[190:193], v[64:67]
	v_mfma_f32_16x16x32_f16 v[116:119], v[202:205], v[170:173], v[116:119]
	v_mfma_f32_16x16x32_f16 v[112:115], v[210:213], v[170:173], v[112:115]
	v_mfma_f32_16x16x32_f16 v[100:103], v[202:205], v[178:181], v[100:103]
	v_mfma_f32_16x16x32_f16 v[96:99], v[210:213], v[178:181], v[96:99]
	v_mfma_f32_16x16x32_f16 v[84:87], v[202:205], v[186:189], v[84:87]
	v_mfma_f32_16x16x32_f16 v[80:83], v[210:213], v[186:189], v[80:83]
	v_mfma_f32_16x16x32_f16 v[68:71], v[202:205], v[194:197], v[68:71]
	v_mfma_f32_16x16x32_f16 v[64:67], v[210:213], v[194:197], v[64:67]
	s_barrier
	s_mov_b32 m0, s29
	ds_read_b128 v[166:169], v152 offset:49152
	ds_read_b128 v[170:173], v152 offset:50176
	ds_read_b128 v[174:177], v152 offset:51200
	ds_read_b128 v[178:181], v152 offset:52224
	ds_read_b128 v[182:185], v152 offset:53248
	ds_read_b128 v[186:189], v152 offset:54272
	ds_read_b128 v[190:193], v152 offset:55296
	ds_read_b128 v[194:197], v152 offset:56320
	global_load_lds_dwordx4 v128, s[74:75]
	s_mov_b32 m0, s30
	s_nop 0
	global_load_lds_dwordx4 v132, s[74:75]
	s_barrier
	s_waitcnt lgkmcnt(0)
	v_mfma_f32_16x16x32_f16 v[60:63], v[144:147], v[166:169], v[60:63]
	v_mfma_f32_16x16x32_f16 v[56:59], v[158:161], v[166:169], v[56:59]
	v_mfma_f32_16x16x32_f16 v[44:47], v[144:147], v[174:177], v[44:47]
	v_mfma_f32_16x16x32_f16 v[40:43], v[158:161], v[174:177], v[40:43]
	v_mfma_f32_16x16x32_f16 v[28:31], v[144:147], v[182:185], v[28:31]
	v_mfma_f32_16x16x32_f16 v[24:27], v[158:161], v[182:185], v[24:27]
	v_mfma_f32_16x16x32_f16 v[12:15], v[144:147], v[190:193], v[12:15]
	v_mfma_f32_16x16x32_f16 v[8:11], v[158:161], v[190:193], v[8:11]
	v_mfma_f32_16x16x32_f16 v[60:63], v[154:157], v[170:173], v[60:63]
	v_mfma_f32_16x16x32_f16 v[56:59], v[162:165], v[170:173], v[56:59]
	v_mfma_f32_16x16x32_f16 v[44:47], v[154:157], v[178:181], v[44:47]
	v_mfma_f32_16x16x32_f16 v[40:43], v[162:165], v[178:181], v[40:43]
	v_mfma_f32_16x16x32_f16 v[28:31], v[154:157], v[186:189], v[28:31]
	v_mfma_f32_16x16x32_f16 v[24:27], v[162:165], v[186:189], v[24:27]
	v_mfma_f32_16x16x32_f16 v[12:15], v[154:157], v[194:197], v[12:15]
	v_mfma_f32_16x16x32_f16 v[8:11], v[162:165], v[194:197], v[8:11]
	s_barrier
	s_add_u32 s18, s18, 0x80080
	s_addc_u32 s19, s19, 0
	s_add_i32 s20, s20, s23
	s_mov_b32 m0, s20
	s_nop 0
	global_load_lds_dwordx4 v130, s[18:19]
	s_add_i32 m0, s20, 0x2000
	s_nop 0
	global_load_lds_dwordx4 v134, s[18:19]
	s_waitcnt vmcnt(6)
	s_barrier
	v_mfma_f32_16x16x32_f16 v[52:55], v[198:201], v[166:169], v[52:55]
	v_mfma_f32_16x16x32_f16 v[48:51], v[206:209], v[166:169], v[48:51]
	v_mfma_f32_16x16x32_f16 v[36:39], v[198:201], v[174:177], v[36:39]
	v_mfma_f32_16x16x32_f16 v[32:35], v[206:209], v[174:177], v[32:35]
	v_mfma_f32_16x16x32_f16 v[20:23], v[198:201], v[182:185], v[20:23]
	v_mfma_f32_16x16x32_f16 v[16:19], v[206:209], v[182:185], v[16:19]
	v_mfma_f32_16x16x32_f16 v[4:7], v[198:201], v[190:193], v[4:7]
	v_mfma_f32_16x16x32_f16 v[0:3], v[206:209], v[190:193], v[0:3]
	v_mfma_f32_16x16x32_f16 v[52:55], v[202:205], v[170:173], v[52:55]
	v_mfma_f32_16x16x32_f16 v[48:51], v[210:213], v[170:173], v[48:51]
	v_mfma_f32_16x16x32_f16 v[36:39], v[202:205], v[178:181], v[36:39]
	v_mfma_f32_16x16x32_f16 v[32:35], v[210:213], v[178:181], v[32:35]
	v_mfma_f32_16x16x32_f16 v[20:23], v[202:205], v[186:189], v[20:23]
	v_mfma_f32_16x16x32_f16 v[16:19], v[210:213], v[186:189], v[16:19]
	v_mfma_f32_16x16x32_f16 v[4:7], v[202:205], v[194:197], v[4:7]
	v_mfma_f32_16x16x32_f16 v[0:3], v[210:213], v[194:197], v[0:3]
	s_barrier
	s_add_i32 s78, s78, 2
	s_add_u32 s16, s16, 0x100
	s_addc_u32 s17, s17, 0
	s_add_u32 s76, s76, 0x100
	s_addc_u32 s77, s77, 0
	s_cmp_gt_u32 s78, 29
	s_cbranch_scc0 .LBB0_197
	s_setprio 0
	v_readlane_b32 s52, v254, 21
	v_readlane_b32 s54, v254, 23
	v_readlane_b32 s55, v254, 24
	v_lshl_add_u32 v154, s14, 8, v148
	v_lshl_or_b32 v144, s4, 8, v150
	v_mov_b64_e32 v[146:147], s[54:55]
	v_mad_i64_i32 v[146:147], s[4:5], v154, s70, v[146:147]
	v_cmp_gt_i32_e32 vcc, s71, v144
	v_ashrrev_i32_e32 v145, 31, v144
	v_readlane_b32 s53, v254, 22
	v_readlane_b32 s56, v254, 25
	v_readlane_b32 s57, v254, 26
	v_readlane_b32 s58, v254, 27
	v_readlane_b32 s59, v254, 28
	v_readlane_b32 s60, v254, 29
	v_readlane_b32 s61, v254, 30
	v_readlane_b32 s62, v254, 31
	v_readlane_b32 s63, v254, 32
	v_readlane_b32 s64, v254, 33
	v_readlane_b32 s65, v254, 34
	v_readlane_b32 s66, v254, 35
	v_readlane_b32 s67, v254, 36
	s_and_saveexec_b64 s[4:5], vcc
	s_cbranch_execz .LBB0_200
	v_cvt_pk_f16_f32 v123, v122, v123
	v_cvt_pk_f16_f32 v122, v120, v121
	v_cvt_pk_f16_f32 v121, v126, v127
	v_cvt_pk_f16_f32 v120, v124, v125
	v_lshl_add_u64 v[124:125], v[144:145], 1, v[146:147]
	global_store_dwordx4 v[124:125], v[120:123], off

.Lprio_y1:
.LBB0_647:
	ds_read_b128 v[80:83], v243
	ds_read_b128 v[88:91], v243 offset:1024
	ds_read_b128 v[96:99], v243 offset:2048
	ds_read_b128 v[100:103], v243 offset:3072
	s_add_u32 s18, s16, 0xfff80080
	s_addc_u32 s19, s17, -1
	s_cmp_eq_u32 s80, 28
	s_cselect_b32 s21, s9, s19
	s_cselect_b32 s20, s31, s18
	s_cselect_b32 s19, s7, s79
	s_cselect_b32 s18, s77, s78
	s_add_i32 m0, s15, 0xc000
	ds_read_b128 v[120:123], v244
	ds_read_b128 v[132:135], v244 offset:1024
	ds_read_b128 v[136:139], v244 offset:2048
	ds_read_b128 v[148:151], v244 offset:3072
	ds_read_b128 v[152:155], v244 offset:4096
	ds_read_b128 v[156:159], v244 offset:5120
	ds_read_b128 v[160:163], v244 offset:6144
	ds_read_b128 v[172:175], v244 offset:7168
	global_load_lds_dwordx4 v212, s[16:17]
	s_add_i32 m0, s15, 0xe000
	s_nop 0
	global_load_lds_dwordx4 v214, s[16:17]
	s_waitcnt lgkmcnt(8)
	s_barrier
	s_waitcnt lgkmcnt(0)
	v_mfma_f32_16x16x32_f16 v[168:171], v[80:83], v[120:123], v[168:171]
	v_mfma_f32_16x16x32_f16 v[164:167], v[96:99], v[120:123], v[164:167]
	v_mfma_f32_16x16x32_f16 v[128:131], v[80:83], v[136:139], v[128:131]
	v_mfma_f32_16x16x32_f16 v[124:127], v[96:99], v[136:139], v[124:127]
	v_mfma_f32_16x16x32_f16 v[108:111], v[80:83], v[152:155], v[108:111]
	v_mfma_f32_16x16x32_f16 v[104:107], v[96:99], v[152:155], v[104:107]
	v_mfma_f32_16x16x32_f16 v[76:79], v[80:83], v[160:163], v[76:79]
	v_mfma_f32_16x16x32_f16 v[72:75], v[96:99], v[160:163], v[72:75]
	v_mfma_f32_16x16x32_f16 v[168:171], v[88:91], v[132:135], v[168:171]
	v_mfma_f32_16x16x32_f16 v[164:167], v[100:103], v[132:135], v[164:167]
	v_mfma_f32_16x16x32_f16 v[128:131], v[88:91], v[148:151], v[128:131]
	v_mfma_f32_16x16x32_f16 v[124:127], v[100:103], v[148:151], v[124:127]
	v_mfma_f32_16x16x32_f16 v[108:111], v[88:91], v[156:159], v[108:111]
	v_mfma_f32_16x16x32_f16 v[104:107], v[100:103], v[156:159], v[104:107]
	v_mfma_f32_16x16x32_f16 v[76:79], v[88:91], v[172:175], v[76:79]
	v_mfma_f32_16x16x32_f16 v[72:75], v[100:103], v[172:175], v[72:75]
	s_barrier
	s_add_i32 s81, s71, s24
	s_add_u32 s72, s18, s4
	s_addc_u32 s73, s19, s5
	s_mov_b32 m0, s81
	ds_read_b128 v[176:179], v245
	ds_read_b128 v[180:183], v245 offset:1024
	ds_read_b128 v[184:187], v245 offset:2048
	ds_read_b128 v[188:191], v245 offset:3072
	global_load_lds_dwordx4 v206, s[18:19]
	s_add_i32 m0, s81, 0x2000
	s_nop 0
	global_load_lds_dwordx4 v210, s[18:19]
	s_barrier
	s_waitcnt lgkmcnt(0)
	v_mfma_f32_16x16x32_f16 v[144:147], v[176:179], v[120:123], v[144:147]
	v_mfma_f32_16x16x32_f16 v[116:119], v[176:179], v[136:139], v[116:119]
	v_mfma_f32_16x16x32_f16 v[112:115], v[184:187], v[136:139], v[112:115]
	v_mfma_f32_16x16x32_f16 v[92:95], v[176:179], v[152:155], v[92:95]
	v_mfma_f32_16x16x32_f16 v[84:87], v[184:187], v[152:155], v[84:87]
	v_mfma_f32_16x16x32_f16 v[68:71], v[176:179], v[160:163], v[68:71]
	v_mfma_f32_16x16x32_f16 v[64:67], v[184:187], v[160:163], v[64:67]
	v_mfma_f32_16x16x32_f16 v[144:147], v[180:183], v[132:135], v[144:147]
	v_mfma_f32_16x16x32_f16 v[120:123], v[184:187], v[120:123], v[140:143]
	v_mfma_f32_16x16x32_f16 v[116:119], v[180:183], v[148:151], v[116:119]
	v_mfma_f32_16x16x32_f16 v[112:115], v[188:191], v[148:151], v[112:115]
	v_mfma_f32_16x16x32_f16 v[92:95], v[180:183], v[156:159], v[92:95]
	v_mfma_f32_16x16x32_f16 v[84:87], v[188:191], v[156:159], v[84:87]
	v_mfma_f32_16x16x32_f16 v[68:71], v[180:183], v[172:175], v[68:71]
	v_mfma_f32_16x16x32_f16 v[64:67], v[188:191], v[172:175], v[64:67]
	v_mfma_f32_16x16x32_f16 v[120:123], v[188:191], v[132:135], v[120:123]
	s_barrier
	s_mov_b32 m0, s15
	s_add_u32 s74, s20, s4
	s_addc_u32 s75, s21, s5
	ds_read_b128 v[132:135], v244 offset:16384
	ds_read_b128 v[136:139], v244 offset:17408
	ds_read_b128 v[140:143], v244 offset:18432
	ds_read_b128 v[148:151], v244 offset:19456
	ds_read_b128 v[152:155], v244 offset:20480
	ds_read_b128 v[156:159], v244 offset:21504
	ds_read_b128 v[160:163], v244 offset:22528
	ds_read_b128 v[172:175], v244 offset:23552
	global_load_lds_dwordx4 v204, s[20:21]
	s_mov_b32 m0, s25
	s_nop 0
	global_load_lds_dwordx4 v208, s[20:21]
	s_barrier
	s_waitcnt lgkmcnt(0)
	v_mfma_f32_16x16x32_f16 v[60:63], v[80:83], v[132:135], v[60:63]
	v_mfma_f32_16x16x32_f16 v[56:59], v[96:99], v[132:135], v[56:59]
	v_mfma_f32_16x16x32_f16 v[44:47], v[80:83], v[140:143], v[44:47]
	v_mfma_f32_16x16x32_f16 v[40:43], v[96:99], v[140:143], v[40:43]
	v_mfma_f32_16x16x32_f16 v[28:31], v[80:83], v[152:155], v[28:31]
	v_mfma_f32_16x16x32_f16 v[24:27], v[96:99], v[152:155], v[24:27]
	v_mfma_f32_16x16x32_f16 v[12:15], v[80:83], v[160:163], v[12:15]
	v_mfma_f32_16x16x32_f16 v[8:11], v[96:99], v[160:163], v[8:11]
	v_mfma_f32_16x16x32_f16 v[60:63], v[88:91], v[136:139], v[60:63]
	v_mfma_f32_16x16x32_f16 v[56:59], v[100:103], v[136:139], v[56:59]
	v_mfma_f32_16x16x32_f16 v[44:47], v[88:91], v[148:151], v[44:47]
	v_mfma_f32_16x16x32_f16 v[40:43], v[100:103], v[148:151], v[40:43]
	v_mfma_f32_16x16x32_f16 v[28:31], v[88:91], v[156:159], v[28:31]
	v_mfma_f32_16x16x32_f16 v[24:27], v[100:103], v[156:159], v[24:27]
	v_mfma_f32_16x16x32_f16 v[12:15], v[88:91], v[172:175], v[12:15]
	v_mfma_f32_16x16x32_f16 v[8:11], v[100:103], v[172:175], v[8:11]
	s_barrier
	s_add_u32 s82, s18, 0x80000
	s_addc_u32 s83, s19, 0
	s_add_i32 s81, s76, s24
	s_mov_b32 m0, s81
	s_nop 0
	global_load_lds_dwordx4 v206, s[82:83]
	s_add_i32 m0, s81, 0x2000
	s_nop 0
	global_load_lds_dwordx4 v210, s[82:83]
	s_waitcnt vmcnt(6)
	s_barrier
	v_mfma_f32_16x16x32_f16 v[52:55], v[176:179], v[132:135], v[52:55]
	v_mfma_f32_16x16x32_f16 v[48:51], v[184:187], v[132:135], v[48:51]
	v_mfma_f32_16x16x32_f16 v[36:39], v[176:179], v[140:143], v[36:39]
	v_mfma_f32_16x16x32_f16 v[32:35], v[184:187], v[140:143], v[32:35]
	v_mfma_f32_16x16x32_f16 v[20:23], v[176:179], v[152:155], v[20:23]
	v_mfma_f32_16x16x32_f16 v[16:19], v[184:187], v[152:155], v[16:19]
	v_mfma_f32_16x16x32_f16 v[4:7], v[176:179], v[160:163], v[4:7]
	v_mfma_f32_16x16x32_f16 v[0:3], v[184:187], v[160:163], v[0:3]
	v_mfma_f32_16x16x32_f16 v[52:55], v[180:183], v[136:139], v[52:55]
	v_mfma_f32_16x16x32_f16 v[48:51], v[188:191], v[136:139], v[48:51]
	v_mfma_f32_16x16x32_f16 v[36:39], v[180:183], v[148:151], v[36:39]
	v_mfma_f32_16x16x32_f16 v[32:35], v[188:191], v[148:151], v[32:35]
	v_mfma_f32_16x16x32_f16 v[20:23], v[180:183], v[156:159], v[20:23]
	v_mfma_f32_16x16x32_f16 v[16:19], v[188:191], v[156:159], v[16:19]
	v_mfma_f32_16x16x32_f16 v[4:7], v[180:183], v[172:175], v[4:7]
	v_mfma_f32_16x16x32_f16 v[0:3], v[188:191], v[172:175], v[0:3]
	s_barrier
	s_add_i32 s81, 0, 0x18000
	v_add_u32_e32 v100, s81, v241
	ds_read_b128 v[80:83], v100
	ds_read_b128 v[88:91], v100 offset:1024
	ds_read_b128 v[96:99], v100 offset:2048
	ds_read_b128 v[100:103], v100 offset:3072
	s_add_u32 s20, s20, 0x80000
	s_addc_u32 s21, s21, 0
	s_mov_b32 m0, s26
	ds_read_b128 v[132:135], v244 offset:32768
	ds_read_b128 v[136:139], v244 offset:33792
	ds_read_b128 v[148:151], v244 offset:34816
	ds_read_b128 v[152:155], v244 offset:35840
	ds_read_b128 v[156:159], v244 offset:36864
	ds_read_b128 v[160:163], v244 offset:37888
	ds_read_b128 v[172:175], v244 offset:38912
	ds_read_b128 v[176:179], v244 offset:39936
	global_load_lds_dwordx4 v204, s[20:21]
	s_mov_b32 m0, s27
	s_nop 0
	global_load_lds_dwordx4 v208, s[20:21]
	s_waitcnt lgkmcnt(8)
	s_barrier
	s_waitcnt lgkmcnt(0)
	v_mfma_f32_16x16x32_f16 v[140:143], v[80:83], v[132:135], v[168:171]
	v_mfma_f32_16x16x32_f16 v[168:171], v[88:91], v[136:139], v[140:143]
	v_mfma_f32_16x16x32_f16 v[140:143], v[96:99], v[132:135], v[164:167]
	v_mfma_f32_16x16x32_f16 v[128:131], v[80:83], v[148:151], v[128:131]
	v_mfma_f32_16x16x32_f16 v[124:127], v[96:99], v[148:151], v[124:127]
	v_mfma_f32_16x16x32_f16 v[108:111], v[80:83], v[156:159], v[108:111]
	v_mfma_f32_16x16x32_f16 v[104:107], v[96:99], v[156:159], v[104:107]
	v_mfma_f32_16x16x32_f16 v[76:79], v[80:83], v[172:175], v[76:79]
	v_mfma_f32_16x16x32_f16 v[72:75], v[96:99], v[172:175], v[72:75]
	v_mfma_f32_16x16x32_f16 v[164:167], v[100:103], v[136:139], v[140:143]
	v_mfma_f32_16x16x32_f16 v[128:131], v[88:91], v[152:155], v[128:131]
	v_mfma_f32_16x16x32_f16 v[124:127], v[100:103], v[152:155], v[124:127]
	v_mfma_f32_16x16x32_f16 v[108:111], v[88:91], v[160:163], v[108:111]
	v_mfma_f32_16x16x32_f16 v[104:107], v[100:103], v[160:163], v[104:107]
	v_mfma_f32_16x16x32_f16 v[76:79], v[88:91], v[176:179], v[76:79]
	v_mfma_f32_16x16x32_f16 v[72:75], v[100:103], v[176:179], v[72:75]
	s_barrier
	s_add_i32 s20, 0, 0x1c000
	v_add_u32_e32 v140, s20, v241
	s_add_i32 s21, s81, s24
	ds_read_b128 v[180:183], v140
	ds_read_b128 v[184:187], v140 offset:1024
	ds_read_b128 v[188:191], v140 offset:2048
	ds_read_b128 v[192:195], v140 offset:3072
	s_mov_b32 m0, s21
	s_nop 0
	global_load_lds_dwordx4 v206, s[72:73]
	s_add_i32 m0, s21, 0x2000
	s_nop 0
	global_load_lds_dwordx4 v210, s[72:73]
	s_barrier
	s_waitcnt lgkmcnt(0)
	v_mfma_f32_16x16x32_f16 v[140:143], v[180:183], v[132:135], v[144:147]
	v_mfma_f32_16x16x32_f16 v[120:123], v[188:191], v[132:135], v[120:123]
	v_mfma_f32_16x16x32_f16 v[116:119], v[180:183], v[148:151], v[116:119]
	v_mfma_f32_16x16x32_f16 v[112:115], v[188:191], v[148:151], v[112:115]
	v_mfma_f32_16x16x32_f16 v[92:95], v[180:183], v[156:159], v[92:95]
	v_mfma_f32_16x16x32_f16 v[84:87], v[188:191], v[156:159], v[84:87]
	v_mfma_f32_16x16x32_f16 v[68:71], v[180:183], v[172:175], v[68:71]
	v_mfma_f32_16x16x32_f16 v[64:67], v[188:191], v[172:175], v[64:67]
	v_mfma_f32_16x16x32_f16 v[144:147], v[184:187], v[136:139], v[140:143]
	v_mfma_f32_16x16x32_f16 v[140:143], v[192:195], v[136:139], v[120:123]
	v_mfma_f32_16x16x32_f16 v[116:119], v[184:187], v[152:155], v[116:119]
	v_mfma_f32_16x16x32_f16 v[112:115], v[192:195], v[152:155], v[112:115]
	v_mfma_f32_16x16x32_f16 v[92:95], v[184:187], v[160:163], v[92:95]
	v_mfma_f32_16x16x32_f16 v[84:87], v[192:195], v[160:163], v[84:87]
	v_mfma_f32_16x16x32_f16 v[68:71], v[184:187], v[176:179], v[68:71]
	v_mfma_f32_16x16x32_f16 v[64:67], v[192:195], v[176:179], v[64:67]
	s_barrier
	s_mov_b32 m0, s35
	ds_read_b128 v[120:123], v244 offset:49152
	ds_read_b128 v[132:135], v244 offset:50176
	ds_read_b128 v[136:139], v244 offset:51200
	ds_read_b128 v[148:151], v244 offset:52224
	ds_read_b128 v[152:155], v244 offset:53248
	ds_read_b128 v[156:159], v244 offset:54272
	ds_read_b128 v[160:163], v244 offset:55296
	ds_read_b128 v[172:175], v244 offset:56320
	global_load_lds_dwordx4 v204, s[74:75]
	s_mov_b32 m0, s68
	s_nop 0
	global_load_lds_dwordx4 v208, s[74:75]
	s_barrier
	s_waitcnt lgkmcnt(0)
	v_mfma_f32_16x16x32_f16 v[60:63], v[80:83], v[120:123], v[60:63]
	v_mfma_f32_16x16x32_f16 v[56:59], v[96:99], v[120:123], v[56:59]
	v_mfma_f32_16x16x32_f16 v[44:47], v[80:83], v[136:139], v[44:47]
	v_mfma_f32_16x16x32_f16 v[40:43], v[96:99], v[136:139], v[40:43]
	v_mfma_f32_16x16x32_f16 v[28:31], v[80:83], v[152:155], v[28:31]
	v_mfma_f32_16x16x32_f16 v[24:27], v[96:99], v[152:155], v[24:27]
	v_mfma_f32_16x16x32_f16 v[12:15], v[80:83], v[160:163], v[12:15]
	v_mfma_f32_16x16x32_f16 v[8:11], v[96:99], v[160:163], v[8:11]
	v_mfma_f32_16x16x32_f16 v[60:63], v[88:91], v[132:135], v[60:63]
	v_mfma_f32_16x16x32_f16 v[56:59], v[100:103], v[132:135], v[56:59]
	v_mfma_f32_16x16x32_f16 v[44:47], v[88:91], v[148:151], v[44:47]
	v_mfma_f32_16x16x32_f16 v[40:43], v[100:103], v[148:151], v[40:43]
	v_mfma_f32_16x16x32_f16 v[28:31], v[88:91], v[156:159], v[28:31]
	v_mfma_f32_16x16x32_f16 v[24:27], v[100:103], v[156:159], v[24:27]
	v_mfma_f32_16x16x32_f16 v[12:15], v[88:91], v[172:175], v[12:15]
	v_mfma_f32_16x16x32_f16 v[8:11], v[100:103], v[172:175], v[8:11]
	s_barrier
	s_add_u32 s18, s18, 0x80080
	s_addc_u32 s19, s19, 0
	s_add_i32 s20, s20, s24
	s_mov_b32 m0, s20
	s_nop 0
	global_load_lds_dwordx4 v206, s[18:19]
	s_add_i32 m0, s20, 0x2000
	s_nop 0
	global_load_lds_dwordx4 v210, s[18:19]
	s_waitcnt vmcnt(6)
	s_barrier
	v_mfma_f32_16x16x32_f16 v[52:55], v[180:183], v[120:123], v[52:55]
	v_mfma_f32_16x16x32_f16 v[48:51], v[188:191], v[120:123], v[48:51]
	v_mfma_f32_16x16x32_f16 v[36:39], v[180:183], v[136:139], v[36:39]
	v_mfma_f32_16x16x32_f16 v[32:35], v[188:191], v[136:139], v[32:35]
	v_mfma_f32_16x16x32_f16 v[20:23], v[180:183], v[152:155], v[20:23]
	v_mfma_f32_16x16x32_f16 v[16:19], v[188:191], v[152:155], v[16:19]
	v_mfma_f32_16x16x32_f16 v[4:7], v[180:183], v[160:163], v[4:7]
	v_mfma_f32_16x16x32_f16 v[0:3], v[188:191], v[160:163], v[0:3]
	v_mfma_f32_16x16x32_f16 v[52:55], v[184:187], v[132:135], v[52:55]
	v_mfma_f32_16x16x32_f16 v[48:51], v[192:195], v[132:135], v[48:51]
	v_mfma_f32_16x16x32_f16 v[36:39], v[184:187], v[148:151], v[36:39]
	v_mfma_f32_16x16x32_f16 v[32:35], v[192:195], v[148:151], v[32:35]
	v_mfma_f32_16x16x32_f16 v[20:23], v[184:187], v[156:159], v[20:23]
	v_mfma_f32_16x16x32_f16 v[16:19], v[192:195], v[156:159], v[16:19]
	v_mfma_f32_16x16x32_f16 v[4:7], v[184:187], v[172:175], v[4:7]
	v_mfma_f32_16x16x32_f16 v[0:3], v[192:195], v[172:175], v[0:3]
	s_barrier
	s_add_i32 s80, s80, 2
	s_add_u32 s16, s16, 0x100
	s_addc_u32 s17, s17, 0
	s_add_u32 s78, s78, 0x100
	s_addc_u32 s79, s79, 0
	s_cmp_gt_u32 s80, 29
	s_cbranch_scc0 .LBB0_647
	s_setprio 0
	s_lshl_b32 s7, s14, 8
	s_add_i32 s9, s7, 0xffffe000
	s_lshr_b32 s9, s9, 11
	s_mulk_i32 s9, 0x1800
	s_addk_i32 s9, 0x1800
	s_cmp_gt_i32 s14, 31
	s_cselect_b32 s16, s9, 0
	s_ashr_i32 s17, s16, 31
	v_lshl_or_b32 v120, s30, 8, v242
	s_lshl_b64 s[16:17], s[16:17], 2
	s_add_u32 s16, s29, s16
	v_ashrrev_i32_e32 v121, 31, v120
	v_add_u32_e32 v122, s7, v240
	s_addc_u32 s17, s34, s17
	v_lshlrev_b64 v[220:221], 1, v[120:121]
	v_ashrrev_i32_e32 v123, 31, v122
	v_lshl_add_u64 v[88:89], v[120:121], 2, s[16:17]
	v_lshl_add_u64 v[120:121], s[40:41], 0, v[220:221]
	v_lshlrev_b64 v[236:237], 12, v[122:123]
	v_lshl_add_u64 v[132:133], v[120:121], 0, v[236:237]
	global_load_dwordx4 v[96:99], v[88:89], off offset:16
	global_load_dwordx4 v[100:103], v[88:89], off
	global_load_dwordx4 v[80:83], v[88:89], off offset:528
	s_nop 0
	global_load_dwordx4 v[88:91], v[88:89], off offset:512
	s_nop 0
	global_load_dwordx4 v[246:249], v[132:133], off nt
	global_load_dwordx4 v[200:203], v[132:133], off offset:256 nt
	v_or_b32_e32 v132, 16, v122
	v_ashrrev_i32_e32 v133, 31, v132
	v_lshlrev_b64 v[234:235], 12, v[132:133]
	v_lshl_add_u64 v[132:133], v[120:121], 0, v[234:235]
	global_load_dwordx4 v[196:199], v[132:133], off nt
	global_load_dwordx4 v[192:195], v[132:133], off offset:256 nt
	v_or_b32_e32 v132, 32, v122
	v_ashrrev_i32_e32 v133, 31, v132
	v_lshlrev_b64 v[232:233], 12, v[132:133]
	v_lshl_add_u64 v[132:133], v[120:121], 0, v[232:233]
	global_load_dwordx4 v[188:191], v[132:133], off nt
	global_load_dwordx4 v[184:187], v[132:133], off offset:256 nt
	v_or_b32_e32 v122, 48, v122
	v_ashrrev_i32_e32 v123, 31, v122
	v_lshlrev_b64 v[230:231], 12, v[122:123]
	v_lshl_add_u64 v[122:123], v[120:121], 0, v[230:231]
	global_load_dwordx4 v[180:183], v[122:123], off nt
	global_load_dwordx4 v[176:179], v[122:123], off offset:256 nt
	s_mov_b64 s[16:17], 0x80000
	v_lshl_add_u64 v[228:229], v[236:237], 0, s[16:17]
	v_lshl_add_u64 v[122:123], v[120:121], 0, v[228:229]
	global_load_dwordx4 v[172:175], v[122:123], off nt
	global_load_dwordx4 v[160:163], v[122:123], off offset:256 nt
	s_mov_b64 s[16:17], 0x90000
	v_lshl_add_u64 v[226:227], v[236:237], 0, s[16:17]
	v_lshl_add_u64 v[122:123], v[120:121], 0, v[226:227]
	global_load_dwordx4 v[156:159], v[122:123], off nt
	global_load_dwordx4 v[152:155], v[122:123], off offset:256 nt
	s_mov_b64 s[16:17], 0xa0000
	v_lshl_add_u64 v[224:225], v[236:237], 0, s[16:17]
	v_lshl_add_u64 v[122:123], v[120:121], 0, v[224:225]
	global_load_dwordx4 v[148:151], v[122:123], off nt
	global_load_dwordx4 v[136:139], v[122:123], off offset:256 nt
	s_mov_b64 s[16:17], 0xb0000
	v_lshl_add_u64 v[222:223], v[236:237], 0, s[16:17]
	v_lshl_add_u64 v[120:121], v[120:121], 0, v[222:223]
	global_load_dwordx4 v[132:135], v[120:121], off nt
	s_nop 0
	global_load_dwordx4 v[120:123], v[120:121], off offset:256 nt
	s_and_b64 vcc, exec, s[2:3]
	s_mov_b32 s30, s6
	s_mov_b32 s14, s8
	s_mov_b64 s[18:19], s[12:13]
	s_mov_b64 s[16:17], s[10:11]
	s_waitcnt vmcnt(0)
	v_cvt_f32_f16_e32 v250, v246
	v_cvt_f32_f16_sdwa v251, v246 dst_sel:DWORD dst_unused:UNUSED_PAD src0_sel:WORD_1
	v_pk_fma_f32 v[168:169], v[168:169], v[100:101], v[250:251]
	s_nop 0
	v_cvt_pk_f16_f32 v246, v168, v169
	v_cvt_f32_f16_e32 v168, v248
	v_cvt_f32_f16_sdwa v169, v248 dst_sel:DWORD dst_unused:UNUSED_PAD src0_sel:WORD_1
	v_pk_fma_f32 v[164:165], v[164:165], v[96:97], v[168:169]
	s_nop 0
	v_cvt_pk_f16_f32 v248, v164, v165
	v_cvt_f32_f16_e32 v164, v247
	v_cvt_f32_f16_sdwa v165, v247 dst_sel:DWORD dst_unused:UNUSED_PAD src0_sel:WORD_1
	v_pk_fma_f32 v[164:165], v[170:171], v[102:103], v[164:165]
	s_nop 0
	v_cvt_pk_f16_f32 v247, v164, v165
	v_cvt_f32_f16_e32 v164, v249
	v_cvt_f32_f16_sdwa v165, v249 dst_sel:DWORD dst_unused:UNUSED_PAD src0_sel:WORD_1
	v_pk_fma_f32 v[164:165], v[166:167], v[98:99], v[164:165]
	s_nop 0
	v_cvt_pk_f16_f32 v249, v164, v165
	v_lshl_add_u64 v[164:165], s[0:1], 0, v[236:237]
	v_lshl_add_u64 v[168:169], v[164:165], 0, v[220:221]
	v_cvt_f32_f16_e32 v164, v200
	v_cvt_f32_f16_sdwa v165, v200 dst_sel:DWORD dst_unused:UNUSED_PAD src0_sel:WORD_1
	global_store_dwordx4 v[168:169], v[246:249], off
	v_pk_fma_f32 v[144:145], v[144:145], v[88:89], v[164:165]
	s_nop 0
	v_cvt_pk_f16_f32 v164, v144, v145
	v_cvt_f32_f16_e32 v144, v202
	v_cvt_f32_f16_sdwa v145, v202 dst_sel:DWORD dst_unused:UNUSED_PAD src0_sel:WORD_1
	v_pk_fma_f32 v[140:141], v[140:141], v[80:81], v[144:145]
	s_nop 0
	v_cvt_pk_f16_f32 v166, v140, v141
	v_cvt_f32_f16_e32 v140, v201
	v_cvt_f32_f16_sdwa v141, v201 dst_sel:DWORD dst_unused:UNUSED_PAD src0_sel:WORD_1
	v_pk_fma_f32 v[140:141], v[146:147], v[90:91], v[140:141]
	s_nop 0
	v_cvt_pk_f16_f32 v165, v140, v141
	v_cvt_f32_f16_e32 v140, v203
	v_cvt_f32_f16_sdwa v141, v203 dst_sel:DWORD dst_unused:UNUSED_PAD src0_sel:WORD_1
	v_pk_fma_f32 v[140:141], v[142:143], v[82:83], v[140:141]
	s_nop 0
	v_cvt_pk_f16_f32 v167, v140, v141
	v_cvt_f32_f16_e32 v140, v196
	v_cvt_f32_f16_sdwa v141, v196 dst_sel:DWORD dst_unused:UNUSED_PAD src0_sel:WORD_1
	global_store_dwordx4 v[168:169], v[164:167], off offset:256
	v_pk_fma_f32 v[128:129], v[128:129], v[100:101], v[140:141]
	s_nop 0
	v_cvt_pk_f16_f32 v140, v128, v129
	v_cvt_f32_f16_e32 v128, v198
	v_cvt_f32_f16_sdwa v129, v198 dst_sel:DWORD dst_unused:UNUSED_PAD src0_sel:WORD_1
	v_pk_fma_f32 v[124:125], v[124:125], v[96:97], v[128:129]
	s_nop 0
	v_cvt_pk_f16_f32 v142, v124, v125
	v_cvt_f32_f16_e32 v124, v197
	v_cvt_f32_f16_sdwa v125, v197 dst_sel:DWORD dst_unused:UNUSED_PAD src0_sel:WORD_1
	v_pk_fma_f32 v[124:125], v[130:131], v[102:103], v[124:125]
	s_nop 0
	v_cvt_pk_f16_f32 v141, v124, v125
	v_cvt_f32_f16_e32 v124, v199
	v_cvt_f32_f16_sdwa v125, v199 dst_sel:DWORD dst_unused:UNUSED_PAD src0_sel:WORD_1
	v_pk_fma_f32 v[124:125], v[126:127], v[98:99], v[124:125]
	s_nop 0
	v_cvt_pk_f16_f32 v143, v124, v125
	v_lshl_add_u64 v[124:125], s[0:1], 0, v[234:235]
	v_lshl_add_u64 v[128:129], v[124:125], 0, v[220:221]
	v_cvt_f32_f16_e32 v124, v192
	v_cvt_f32_f16_sdwa v125, v192 dst_sel:DWORD dst_unused:UNUSED_PAD src0_sel:WORD_1
	global_store_dwordx4 v[128:129], v[140:143], off
	v_pk_fma_f32 v[116:117], v[116:117], v[88:89], v[124:125]
	s_nop 0
	v_cvt_pk_f16_f32 v124, v116, v117
	v_cvt_f32_f16_e32 v116, v194
	v_cvt_f32_f16_sdwa v117, v194 dst_sel:DWORD dst_unused:UNUSED_PAD src0_sel:WORD_1
	v_pk_fma_f32 v[112:113], v[112:113], v[80:81], v[116:117]
	s_nop 0
	v_cvt_pk_f16_f32 v126, v112, v113
	v_cvt_f32_f16_e32 v112, v193
	v_cvt_f32_f16_sdwa v113, v193 dst_sel:DWORD dst_unused:UNUSED_PAD src0_sel:WORD_1
	v_pk_fma_f32 v[112:113], v[118:119], v[90:91], v[112:113]
	s_nop 0
	v_cvt_pk_f16_f32 v125, v112, v113
	v_cvt_f32_f16_e32 v112, v195
	v_cvt_f32_f16_sdwa v113, v195 dst_sel:DWORD dst_unused:UNUSED_PAD src0_sel:WORD_1
	v_pk_fma_f32 v[112:113], v[114:115], v[82:83], v[112:113]
	s_nop 0
	v_cvt_pk_f16_f32 v127, v112, v113
	v_cvt_f32_f16_e32 v112, v188
	v_cvt_f32_f16_sdwa v113, v188 dst_sel:DWORD dst_unused:UNUSED_PAD src0_sel:WORD_1
	global_store_dwordx4 v[128:129], v[124:127], off offset:256
	v_pk_fma_f32 v[108:109], v[108:109], v[100:101], v[112:113]
	s_nop 0
	v_cvt_pk_f16_f32 v112, v108, v109
	v_cvt_f32_f16_e32 v108, v190
	v_cvt_f32_f16_sdwa v109, v190 dst_sel:DWORD dst_unused:UNUSED_PAD src0_sel:WORD_1
	v_pk_fma_f32 v[104:105], v[104:105], v[96:97], v[108:109]
	s_nop 0
	v_cvt_pk_f16_f32 v114, v104, v105
	v_cvt_f32_f16_e32 v104, v189
	v_cvt_f32_f16_sdwa v105, v189 dst_sel:DWORD dst_unused:UNUSED_PAD src0_sel:WORD_1
	v_pk_fma_f32 v[104:105], v[110:111], v[102:103], v[104:105]
	s_nop 0
	v_cvt_pk_f16_f32 v113, v104, v105
	v_cvt_f32_f16_e32 v104, v191
	v_cvt_f32_f16_sdwa v105, v191 dst_sel:DWORD dst_unused:UNUSED_PAD src0_sel:WORD_1
	v_pk_fma_f32 v[104:105], v[106:107], v[98:99], v[104:105]
	s_nop 0
	v_cvt_pk_f16_f32 v115, v104, v105
	v_lshl_add_u64 v[104:105], s[0:1], 0, v[232:233]
	v_lshl_add_u64 v[108:109], v[104:105], 0, v[220:221]
	v_cvt_f32_f16_e32 v104, v184
	v_cvt_f32_f16_sdwa v105, v184 dst_sel:DWORD dst_unused:UNUSED_PAD src0_sel:WORD_1
	global_store_dwordx4 v[108:109], v[112:115], off
	v_pk_fma_f32 v[92:93], v[92:93], v[88:89], v[104:105]
	s_nop 0
	v_cvt_pk_f16_f32 v104, v92, v93
	v_cvt_f32_f16_e32 v92, v186
	v_cvt_f32_f16_sdwa v93, v186 dst_sel:DWORD dst_unused:UNUSED_PAD src0_sel:WORD_1
	v_pk_fma_f32 v[84:85], v[84:85], v[80:81], v[92:93]
	s_nop 0
	v_cvt_pk_f16_f32 v106, v84, v85
	v_cvt_f32_f16_e32 v84, v185
	v_cvt_f32_f16_sdwa v85, v185 dst_sel:DWORD dst_unused:UNUSED_PAD src0_sel:WORD_1
	v_pk_fma_f32 v[84:85], v[94:95], v[90:91], v[84:85]
	s_nop 0
	v_cvt_pk_f16_f32 v105, v84, v85
	v_cvt_f32_f16_e32 v84, v187
	v_cvt_f32_f16_sdwa v85, v187 dst_sel:DWORD dst_unused:UNUSED_PAD src0_sel:WORD_1
	v_pk_fma_f32 v[84:85], v[86:87], v[82:83], v[84:85]
	s_nop 0
	v_cvt_pk_f16_f32 v107, v84, v85
	v_cvt_f32_f16_e32 v84, v180
	v_cvt_f32_f16_sdwa v85, v180 dst_sel:DWORD dst_unused:UNUSED_PAD src0_sel:WORD_1
	global_store_dwordx4 v[108:109], v[104:107], off offset:256
	v_pk_fma_f32 v[76:77], v[76:77], v[100:101], v[84:85]
	s_nop 0
	v_cvt_pk_f16_f32 v84, v76, v77
	v_cvt_f32_f16_e32 v76, v182
	v_cvt_f32_f16_sdwa v77, v182 dst_sel:DWORD dst_unused:UNUSED_PAD src0_sel:WORD_1
	v_pk_fma_f32 v[72:73], v[72:73], v[96:97], v[76:77]
	s_nop 0
	v_cvt_pk_f16_f32 v86, v72, v73
	v_cvt_f32_f16_e32 v72, v181
	v_cvt_f32_f16_sdwa v73, v181 dst_sel:DWORD dst_unused:UNUSED_PAD src0_sel:WORD_1
	v_pk_fma_f32 v[72:73], v[78:79], v[102:103], v[72:73]
	s_nop 0
	v_cvt_pk_f16_f32 v85, v72, v73
	v_cvt_f32_f16_e32 v72, v183
	v_cvt_f32_f16_sdwa v73, v183 dst_sel:DWORD dst_unused:UNUSED_PAD src0_sel:WORD_1
	v_pk_fma_f32 v[72:73], v[74:75], v[98:99], v[72:73]
	s_nop 0
	v_cvt_pk_f16_f32 v87, v72, v73
	v_lshl_add_u64 v[72:73], s[0:1], 0, v[230:231]
	v_lshl_add_u64 v[76:77], v[72:73], 0, v[220:221]
	v_cvt_f32_f16_e32 v72, v176
	v_cvt_f32_f16_sdwa v73, v176 dst_sel:DWORD dst_unused:UNUSED_PAD src0_sel:WORD_1
	global_store_dwordx4 v[76:77], v[84:87], off
	v_pk_fma_f32 v[68:69], v[68:69], v[88:89], v[72:73]
	s_nop 0
	v_cvt_pk_f16_f32 v72, v68, v69
	v_cvt_f32_f16_e32 v68, v178
	v_cvt_f32_f16_sdwa v69, v178 dst_sel:DWORD dst_unused:UNUSED_PAD src0_sel:WORD_1
	v_pk_fma_f32 v[64:65], v[64:65], v[80:81], v[68:69]
	s_nop 0
	v_cvt_pk_f16_f32 v74, v64, v65
	v_cvt_f32_f16_e32 v64, v177
	v_cvt_f32_f16_sdwa v65, v177 dst_sel:DWORD dst_unused:UNUSED_PAD src0_sel:WORD_1
	v_pk_fma_f32 v[64:65], v[70:71], v[90:91], v[64:65]
	s_nop 0
	v_cvt_pk_f16_f32 v73, v64, v65
	v_cvt_f32_f16_e32 v64, v179
	v_cvt_f32_f16_sdwa v65, v179 dst_sel:DWORD dst_unused:UNUSED_PAD src0_sel:WORD_1
	v_pk_fma_f32 v[64:65], v[66:67], v[82:83], v[64:65]
	s_nop 0
	v_cvt_pk_f16_f32 v75, v64, v65
	v_cvt_f32_f16_e32 v64, v172
	v_cvt_f32_f16_sdwa v65, v172 dst_sel:DWORD dst_unused:UNUSED_PAD src0_sel:WORD_1
	global_store_dwordx4 v[76:77], v[72:75], off offset:256
	v_pk_fma_f32 v[60:61], v[60:61], v[100:101], v[64:65]
	s_nop 0
	v_cvt_pk_f16_f32 v64, v60, v61
	v_cvt_f32_f16_e32 v60, v174
	v_cvt_f32_f16_sdwa v61, v174 dst_sel:DWORD dst_unused:UNUSED_PAD src0_sel:WORD_1
	v_pk_fma_f32 v[56:57], v[56:57], v[96:97], v[60:61]
	s_nop 0
	v_cvt_pk_f16_f32 v66, v56, v57
	v_cvt_f32_f16_e32 v56, v173
	v_cvt_f32_f16_sdwa v57, v173 dst_sel:DWORD dst_unused:UNUSED_PAD src0_sel:WORD_1
	v_pk_fma_f32 v[56:57], v[62:63], v[102:103], v[56:57]
	s_nop 0
	v_cvt_pk_f16_f32 v65, v56, v57
	v_cvt_f32_f16_e32 v56, v175
	v_cvt_f32_f16_sdwa v57, v175 dst_sel:DWORD dst_unused:UNUSED_PAD src0_sel:WORD_1
	v_pk_fma_f32 v[56:57], v[58:59], v[98:99], v[56:57]
	s_nop 0
	v_cvt_pk_f16_f32 v67, v56, v57
	v_lshl_add_u64 v[56:57], s[0:1], 0, v[228:229]
	v_lshl_add_u64 v[60:61], v[56:57], 0, v[220:221]
	v_cvt_f32_f16_e32 v56, v160
	v_cvt_f32_f16_sdwa v57, v160 dst_sel:DWORD dst_unused:UNUSED_PAD src0_sel:WORD_1
	global_store_dwordx4 v[60:61], v[64:67], off
	v_pk_fma_f32 v[52:53], v[52:53], v[88:89], v[56:57]
	s_nop 0
	v_cvt_pk_f16_f32 v56, v52, v53
	v_cvt_f32_f16_e32 v52, v162
	v_cvt_f32_f16_sdwa v53, v162 dst_sel:DWORD dst_unused:UNUSED_PAD src0_sel:WORD_1
	v_pk_fma_f32 v[48:49], v[48:49], v[80:81], v[52:53]
	s_nop 0
	v_cvt_pk_f16_f32 v58, v48, v49
	v_cvt_f32_f16_e32 v48, v161
	v_cvt_f32_f16_sdwa v49, v161 dst_sel:DWORD dst_unused:UNUSED_PAD src0_sel:WORD_1
	v_pk_fma_f32 v[48:49], v[54:55], v[90:91], v[48:49]
	s_nop 0
	v_cvt_pk_f16_f32 v57, v48, v49
	v_cvt_f32_f16_e32 v48, v163
	v_cvt_f32_f16_sdwa v49, v163 dst_sel:DWORD dst_unused:UNUSED_PAD src0_sel:WORD_1
	v_pk_fma_f32 v[48:49], v[50:51], v[82:83], v[48:49]
	s_nop 0
	v_cvt_pk_f16_f32 v59, v48, v49
	v_cvt_f32_f16_e32 v48, v156
	v_cvt_f32_f16_sdwa v49, v156 dst_sel:DWORD dst_unused:UNUSED_PAD src0_sel:WORD_1
	global_store_dwordx4 v[60:61], v[56:59], off offset:256
	v_pk_fma_f32 v[44:45], v[44:45], v[100:101], v[48:49]
	s_nop 0
	v_cvt_pk_f16_f32 v48, v44, v45
	v_cvt_f32_f16_e32 v44, v158
	v_cvt_f32_f16_sdwa v45, v158 dst_sel:DWORD dst_unused:UNUSED_PAD src0_sel:WORD_1
	v_pk_fma_f32 v[40:41], v[40:41], v[96:97], v[44:45]
	s_nop 0
	v_cvt_pk_f16_f32 v50, v40, v41
	v_cvt_f32_f16_e32 v40, v157
	v_cvt_f32_f16_sdwa v41, v157 dst_sel:DWORD dst_unused:UNUSED_PAD src0_sel:WORD_1
	v_pk_fma_f32 v[40:41], v[46:47], v[102:103], v[40:41]
	s_nop 0
	v_cvt_pk_f16_f32 v49, v40, v41
	v_cvt_f32_f16_e32 v40, v159
	v_cvt_f32_f16_sdwa v41, v159 dst_sel:DWORD dst_unused:UNUSED_PAD src0_sel:WORD_1
	v_pk_fma_f32 v[40:41], v[42:43], v[98:99], v[40:41]
	s_nop 0
	v_cvt_pk_f16_f32 v51, v40, v41
	v_lshl_add_u64 v[40:41], s[0:1], 0, v[226:227]
	v_lshl_add_u64 v[44:45], v[40:41], 0, v[220:221]
	v_cvt_f32_f16_e32 v40, v152
	v_cvt_f32_f16_sdwa v41, v152 dst_sel:DWORD dst_unused:UNUSED_PAD src0_sel:WORD_1
	global_store_dwordx4 v[44:45], v[48:51], off
	v_pk_fma_f32 v[36:37], v[36:37], v[88:89], v[40:41]
	s_nop 0
	v_cvt_pk_f16_f32 v40, v36, v37
	v_cvt_f32_f16_e32 v36, v154
	v_cvt_f32_f16_sdwa v37, v154 dst_sel:DWORD dst_unused:UNUSED_PAD src0_sel:WORD_1
	v_pk_fma_f32 v[32:33], v[32:33], v[80:81], v[36:37]
	s_nop 0
	v_cvt_pk_f16_f32 v42, v32, v33
	v_cvt_f32_f16_e32 v32, v153
	v_cvt_f32_f16_sdwa v33, v153 dst_sel:DWORD dst_unused:UNUSED_PAD src0_sel:WORD_1
	v_pk_fma_f32 v[32:33], v[38:39], v[90:91], v[32:33]
	s_nop 0
	v_cvt_pk_f16_f32 v41, v32, v33
	v_cvt_f32_f16_e32 v32, v155
	v_cvt_f32_f16_sdwa v33, v155 dst_sel:DWORD dst_unused:UNUSED_PAD src0_sel:WORD_1
	v_pk_fma_f32 v[32:33], v[34:35], v[82:83], v[32:33]
	s_nop 0
	v_cvt_pk_f16_f32 v43, v32, v33
	v_cvt_f32_f16_e32 v32, v148
	v_cvt_f32_f16_sdwa v33, v148 dst_sel:DWORD dst_unused:UNUSED_PAD src0_sel:WORD_1
	global_store_dwordx4 v[44:45], v[40:43], off offset:256
	v_pk_fma_f32 v[28:29], v[28:29], v[100:101], v[32:33]
	s_nop 0
	v_cvt_pk_f16_f32 v32, v28, v29
	v_cvt_f32_f16_e32 v28, v150
	v_cvt_f32_f16_sdwa v29, v150 dst_sel:DWORD dst_unused:UNUSED_PAD src0_sel:WORD_1
	v_pk_fma_f32 v[24:25], v[24:25], v[96:97], v[28:29]
	s_nop 0
	v_cvt_pk_f16_f32 v34, v24, v25
	v_cvt_f32_f16_e32 v24, v149
	v_cvt_f32_f16_sdwa v25, v149 dst_sel:DWORD dst_unused:UNUSED_PAD src0_sel:WORD_1
	v_pk_fma_f32 v[24:25], v[30:31], v[102:103], v[24:25]
	s_nop 0
	v_cvt_pk_f16_f32 v33, v24, v25
	v_cvt_f32_f16_e32 v24, v151
	v_cvt_f32_f16_sdwa v25, v151 dst_sel:DWORD dst_unused:UNUSED_PAD src0_sel:WORD_1
	v_pk_fma_f32 v[24:25], v[26:27], v[98:99], v[24:25]
	s_nop 0
	v_cvt_pk_f16_f32 v35, v24, v25
	v_lshl_add_u64 v[24:25], s[0:1], 0, v[224:225]
	v_lshl_add_u64 v[28:29], v[24:25], 0, v[220:221]
	v_cvt_f32_f16_e32 v24, v136
	v_cvt_f32_f16_sdwa v25, v136 dst_sel:DWORD dst_unused:UNUSED_PAD src0_sel:WORD_1
	global_store_dwordx4 v[28:29], v[32:35], off
	v_pk_fma_f32 v[20:21], v[20:21], v[88:89], v[24:25]
	s_nop 0
	v_cvt_pk_f16_f32 v24, v20, v21
	v_cvt_f32_f16_e32 v20, v138
	v_cvt_f32_f16_sdwa v21, v138 dst_sel:DWORD dst_unused:UNUSED_PAD src0_sel:WORD_1
	v_pk_fma_f32 v[16:17], v[16:17], v[80:81], v[20:21]
	s_nop 0
	v_cvt_pk_f16_f32 v26, v16, v17
	v_cvt_f32_f16_e32 v16, v137
	v_cvt_f32_f16_sdwa v17, v137 dst_sel:DWORD dst_unused:UNUSED_PAD src0_sel:WORD_1
	v_pk_fma_f32 v[16:17], v[22:23], v[90:91], v[16:17]
	s_nop 0
	v_cvt_pk_f16_f32 v25, v16, v17
	v_cvt_f32_f16_e32 v16, v139
	v_cvt_f32_f16_sdwa v17, v139 dst_sel:DWORD dst_unused:UNUSED_PAD src0_sel:WORD_1
	v_pk_fma_f32 v[16:17], v[18:19], v[82:83], v[16:17]
	s_nop 0
	v_cvt_pk_f16_f32 v27, v16, v17
	v_cvt_f32_f16_e32 v16, v132
	v_cvt_f32_f16_sdwa v17, v132 dst_sel:DWORD dst_unused:UNUSED_PAD src0_sel:WORD_1
	global_store_dwordx4 v[28:29], v[24:27], off offset:256
	v_pk_fma_f32 v[12:13], v[12:13], v[100:101], v[16:17]
	s_nop 0
	v_cvt_pk_f16_f32 v16, v12, v13
	v_cvt_f32_f16_e32 v12, v134
	v_cvt_f32_f16_sdwa v13, v134 dst_sel:DWORD dst_unused:UNUSED_PAD src0_sel:WORD_1
	v_pk_fma_f32 v[8:9], v[8:9], v[96:97], v[12:13]
	s_nop 0
	v_cvt_pk_f16_f32 v18, v8, v9
	v_cvt_f32_f16_e32 v8, v133
	v_cvt_f32_f16_sdwa v9, v133 dst_sel:DWORD dst_unused:UNUSED_PAD src0_sel:WORD_1
	v_pk_fma_f32 v[8:9], v[14:15], v[102:103], v[8:9]
	s_nop 0
	v_cvt_pk_f16_f32 v17, v8, v9
	v_cvt_f32_f16_e32 v8, v135
	v_cvt_f32_f16_sdwa v9, v135 dst_sel:DWORD dst_unused:UNUSED_PAD src0_sel:WORD_1
	v_pk_fma_f32 v[8:9], v[10:11], v[98:99], v[8:9]
	s_nop 0
	v_cvt_pk_f16_f32 v19, v8, v9
	v_lshl_add_u64 v[8:9], s[0:1], 0, v[222:223]
	v_lshl_add_u64 v[12:13], v[8:9], 0, v[220:221]
	v_cvt_f32_f16_e32 v8, v120
	v_cvt_f32_f16_sdwa v9, v120 dst_sel:DWORD dst_unused:UNUSED_PAD src0_sel:WORD_1
	global_store_dwordx4 v[12:13], v[16:19], off
	v_pk_fma_f32 v[4:5], v[4:5], v[88:89], v[8:9]
	s_nop 0
	v_cvt_pk_f16_f32 v8, v4, v5
	v_cvt_f32_f16_e32 v4, v122
	v_cvt_f32_f16_sdwa v5, v122 dst_sel:DWORD dst_unused:UNUSED_PAD src0_sel:WORD_1
	v_pk_fma_f32 v[0:1], v[0:1], v[80:81], v[4:5]
	s_nop 0
	v_cvt_pk_f16_f32 v10, v0, v1
	v_cvt_f32_f16_e32 v0, v121
	v_cvt_f32_f16_sdwa v1, v121 dst_sel:DWORD dst_unused:UNUSED_PAD src0_sel:WORD_1
	v_pk_fma_f32 v[0:1], v[6:7], v[90:91], v[0:1]
	s_nop 0
	v_cvt_pk_f16_f32 v9, v0, v1
	v_cvt_f32_f16_e32 v0, v123
	v_cvt_f32_f16_sdwa v1, v123 dst_sel:DWORD dst_unused:UNUSED_PAD src0_sel:WORD_1
	v_pk_fma_f32 v[0:1], v[2:3], v[82:83], v[0:1]
	s_nop 0
	v_cvt_pk_f16_f32 v11, v0, v1
	global_store_dwordx4 v[12:13], v[8:11], off offset:256
	s_cbranch_vccz .LBB0_640
	s_waitcnt vmcnt(0)
	s_cmpk_gt_u32 s22, 0xff
	s_cbranch_scc1 .LBB0_651
	s_barrier

.Lprio_y3:
.LBB0_1185:
	ds_read_b128 v[88:91], v243
	ds_read_b128 v[96:99], v243 offset:1024
	ds_read_b128 v[108:111], v243 offset:2048
	ds_read_b128 v[116:119], v243 offset:3072
	s_add_u32 s26, s24, 0xfff80080
	s_addc_u32 s27, s25, -1
	s_cmp_eq_u32 s64, 28
	s_cselect_b32 s29, s17, s27
	s_cselect_b32 s28, s31, s26
	s_cselect_b32 s27, s15, s63
	s_cselect_b32 s26, s61, s62
	s_add_i32 m0, s23, 0xc000
	ds_read_b128 v[128:131], v244
	ds_read_b128 v[136:139], v244 offset:1024
	ds_read_b128 v[144:147], v244 offset:2048
	ds_read_b128 v[148:151], v244 offset:3072
	ds_read_b128 v[152:155], v244 offset:4096
	ds_read_b128 v[164:167], v244 offset:5120
	ds_read_b128 v[168:171], v244 offset:6144
	ds_read_b128 v[172:175], v244 offset:7168
	global_load_lds_dwordx4 v212, s[24:25]
	s_add_i32 m0, s23, 0xe000
	s_nop 0
	global_load_lds_dwordx4 v214, s[24:25]
	s_waitcnt lgkmcnt(8)
	s_barrier
	s_waitcnt lgkmcnt(0)
	v_mfma_f32_16x16x32_f16 v[160:163], v[88:91], v[128:131], v[160:163]
	v_mfma_f32_16x16x32_f16 v[156:159], v[108:111], v[128:131], v[156:159]
	v_mfma_f32_16x16x32_f16 v[124:127], v[88:91], v[144:147], v[124:127]
	v_mfma_f32_16x16x32_f16 v[120:123], v[108:111], v[144:147], v[120:123]
	v_mfma_f32_16x16x32_f16 v[100:103], v[88:91], v[152:155], v[100:103]
	v_mfma_f32_16x16x32_f16 v[92:95], v[108:111], v[152:155], v[92:95]
	v_mfma_f32_16x16x32_f16 v[76:79], v[88:91], v[168:171], v[76:79]
	v_mfma_f32_16x16x32_f16 v[72:75], v[108:111], v[168:171], v[72:75]
	v_mfma_f32_16x16x32_f16 v[160:163], v[96:99], v[136:139], v[160:163]
	v_mfma_f32_16x16x32_f16 v[156:159], v[116:119], v[136:139], v[156:159]
	v_mfma_f32_16x16x32_f16 v[124:127], v[96:99], v[148:151], v[124:127]
	v_mfma_f32_16x16x32_f16 v[120:123], v[116:119], v[148:151], v[120:123]
	v_mfma_f32_16x16x32_f16 v[100:103], v[96:99], v[164:167], v[100:103]
	v_mfma_f32_16x16x32_f16 v[92:95], v[116:119], v[164:167], v[92:95]
	v_mfma_f32_16x16x32_f16 v[76:79], v[96:99], v[172:175], v[76:79]
	v_mfma_f32_16x16x32_f16 v[72:75], v[116:119], v[172:175], v[72:75]
	s_barrier
	s_add_i32 s65, s59, s44
	s_add_u32 s72, s26, s6
	s_addc_u32 s73, s27, s7
	s_mov_b32 m0, s65
	ds_read_b128 v[176:179], v245
	ds_read_b128 v[180:183], v245 offset:1024
	ds_read_b128 v[184:187], v245 offset:2048
	ds_read_b128 v[188:191], v245 offset:3072
	global_load_lds_dwordx4 v206, s[26:27]
	s_add_i32 m0, s65, 0x2000
	s_nop 0
	global_load_lds_dwordx4 v210, s[26:27]
	s_barrier
	s_waitcnt lgkmcnt(0)
	v_mfma_f32_16x16x32_f16 v[140:143], v[176:179], v[128:131], v[140:143]
	v_mfma_f32_16x16x32_f16 v[112:115], v[176:179], v[144:147], v[112:115]
	v_mfma_f32_16x16x32_f16 v[104:107], v[184:187], v[144:147], v[104:107]
	v_mfma_f32_16x16x32_f16 v[84:87], v[176:179], v[152:155], v[84:87]
	v_mfma_f32_16x16x32_f16 v[80:83], v[184:187], v[152:155], v[80:83]
	v_mfma_f32_16x16x32_f16 v[68:71], v[176:179], v[168:171], v[68:71]
	v_mfma_f32_16x16x32_f16 v[64:67], v[184:187], v[168:171], v[64:67]
	v_mfma_f32_16x16x32_f16 v[140:143], v[180:183], v[136:139], v[140:143]
	v_mfma_f32_16x16x32_f16 v[128:131], v[184:187], v[128:131], v[132:135]
	v_mfma_f32_16x16x32_f16 v[112:115], v[180:183], v[148:151], v[112:115]
	v_mfma_f32_16x16x32_f16 v[104:107], v[188:191], v[148:151], v[104:107]
	v_mfma_f32_16x16x32_f16 v[84:87], v[180:183], v[164:167], v[84:87]
	v_mfma_f32_16x16x32_f16 v[80:83], v[188:191], v[164:167], v[80:83]
	v_mfma_f32_16x16x32_f16 v[68:71], v[180:183], v[172:175], v[68:71]
	v_mfma_f32_16x16x32_f16 v[64:67], v[188:191], v[172:175], v[64:67]
	v_mfma_f32_16x16x32_f16 v[128:131], v[188:191], v[136:139], v[128:131]
	s_barrier
	s_mov_b32 m0, s23
	s_add_u32 s74, s28, s6
	s_addc_u32 s75, s29, s7
	ds_read_b128 v[132:135], v244 offset:16384
	ds_read_b128 v[136:139], v244 offset:17408
	ds_read_b128 v[144:147], v244 offset:18432
	ds_read_b128 v[148:151], v244 offset:19456
	ds_read_b128 v[152:155], v244 offset:20480
	ds_read_b128 v[164:167], v244 offset:21504
	ds_read_b128 v[168:171], v244 offset:22528
	ds_read_b128 v[172:175], v244 offset:23552
	global_load_lds_dwordx4 v204, s[28:29]
	s_mov_b32 m0, s45
	s_nop 0
	global_load_lds_dwordx4 v208, s[28:29]
	s_barrier
	s_waitcnt lgkmcnt(0)
	v_mfma_f32_16x16x32_f16 v[60:63], v[88:91], v[132:135], v[60:63]
	v_mfma_f32_16x16x32_f16 v[56:59], v[108:111], v[132:135], v[56:59]
	v_mfma_f32_16x16x32_f16 v[44:47], v[88:91], v[144:147], v[44:47]
	v_mfma_f32_16x16x32_f16 v[40:43], v[108:111], v[144:147], v[40:43]
	v_mfma_f32_16x16x32_f16 v[28:31], v[88:91], v[152:155], v[28:31]
	v_mfma_f32_16x16x32_f16 v[24:27], v[108:111], v[152:155], v[24:27]
	v_mfma_f32_16x16x32_f16 v[12:15], v[88:91], v[168:171], v[12:15]
	v_mfma_f32_16x16x32_f16 v[8:11], v[108:111], v[168:171], v[8:11]
	v_mfma_f32_16x16x32_f16 v[60:63], v[96:99], v[136:139], v[60:63]
	v_mfma_f32_16x16x32_f16 v[56:59], v[116:119], v[136:139], v[56:59]
	v_mfma_f32_16x16x32_f16 v[44:47], v[96:99], v[148:151], v[44:47]
	v_mfma_f32_16x16x32_f16 v[40:43], v[116:119], v[148:151], v[40:43]
	v_mfma_f32_16x16x32_f16 v[28:31], v[96:99], v[164:167], v[28:31]
	v_mfma_f32_16x16x32_f16 v[24:27], v[116:119], v[164:167], v[24:27]
	v_mfma_f32_16x16x32_f16 v[12:15], v[96:99], v[172:175], v[12:15]
	v_mfma_f32_16x16x32_f16 v[8:11], v[116:119], v[172:175], v[8:11]
	s_barrier
	s_add_u32 s66, s26, 0x80000
	s_addc_u32 s67, s27, 0
	s_add_i32 s65, s60, s44
	s_mov_b32 m0, s65
	s_nop 0
	global_load_lds_dwordx4 v206, s[66:67]
	s_add_i32 m0, s65, 0x2000
	s_nop 0
	global_load_lds_dwordx4 v210, s[66:67]
	s_waitcnt vmcnt(6)
	s_barrier
	v_mfma_f32_16x16x32_f16 v[52:55], v[176:179], v[132:135], v[52:55]
	v_mfma_f32_16x16x32_f16 v[48:51], v[184:187], v[132:135], v[48:51]
	v_mfma_f32_16x16x32_f16 v[36:39], v[176:179], v[144:147], v[36:39]
	v_mfma_f32_16x16x32_f16 v[32:35], v[184:187], v[144:147], v[32:35]
	v_mfma_f32_16x16x32_f16 v[20:23], v[176:179], v[152:155], v[20:23]
	v_mfma_f32_16x16x32_f16 v[16:19], v[184:187], v[152:155], v[16:19]
	v_mfma_f32_16x16x32_f16 v[4:7], v[176:179], v[168:171], v[4:7]
	v_mfma_f32_16x16x32_f16 v[0:3], v[184:187], v[168:171], v[0:3]
	v_mfma_f32_16x16x32_f16 v[52:55], v[180:183], v[136:139], v[52:55]
	v_mfma_f32_16x16x32_f16 v[48:51], v[188:191], v[136:139], v[48:51]
	v_mfma_f32_16x16x32_f16 v[36:39], v[180:183], v[148:151], v[36:39]
	v_mfma_f32_16x16x32_f16 v[32:35], v[188:191], v[148:151], v[32:35]
	v_mfma_f32_16x16x32_f16 v[20:23], v[180:183], v[164:167], v[20:23]
	v_mfma_f32_16x16x32_f16 v[16:19], v[188:191], v[164:167], v[16:19]
	v_mfma_f32_16x16x32_f16 v[4:7], v[180:183], v[172:175], v[4:7]
	v_mfma_f32_16x16x32_f16 v[0:3], v[188:191], v[172:175], v[0:3]
	s_barrier
	s_add_i32 s65, 0, 0x18000
	v_add_u32_e32 v116, s65, v241
	ds_read_b128 v[88:91], v116
	ds_read_b128 v[96:99], v116 offset:1024
	ds_read_b128 v[108:111], v116 offset:2048
	ds_read_b128 v[116:119], v116 offset:3072
	s_add_u32 s28, s28, 0x80000
	s_addc_u32 s29, s29, 0
	s_mov_b32 m0, s48
	ds_read_b128 v[132:135], v244 offset:32768
	ds_read_b128 v[136:139], v244 offset:33792
	ds_read_b128 v[144:147], v244 offset:34816
	ds_read_b128 v[148:151], v244 offset:35840
	ds_read_b128 v[152:155], v244 offset:36864
	ds_read_b128 v[164:167], v244 offset:37888
	ds_read_b128 v[168:171], v244 offset:38912
	ds_read_b128 v[172:175], v244 offset:39936
	global_load_lds_dwordx4 v204, s[28:29]
	s_mov_b32 m0, s49
	s_nop 0
	global_load_lds_dwordx4 v208, s[28:29]
	s_waitcnt lgkmcnt(8)
	s_barrier
	s_waitcnt lgkmcnt(0)
	v_mfma_f32_16x16x32_f16 v[160:163], v[88:91], v[132:135], v[160:163]
	v_mfma_f32_16x16x32_f16 v[156:159], v[108:111], v[132:135], v[156:159]
	v_mfma_f32_16x16x32_f16 v[124:127], v[88:91], v[144:147], v[124:127]
	v_mfma_f32_16x16x32_f16 v[120:123], v[108:111], v[144:147], v[120:123]
	v_mfma_f32_16x16x32_f16 v[100:103], v[88:91], v[152:155], v[100:103]
	v_mfma_f32_16x16x32_f16 v[92:95], v[108:111], v[152:155], v[92:95]
	v_mfma_f32_16x16x32_f16 v[76:79], v[88:91], v[168:171], v[76:79]
	v_mfma_f32_16x16x32_f16 v[72:75], v[108:111], v[168:171], v[72:75]
	v_mfma_f32_16x16x32_f16 v[160:163], v[96:99], v[136:139], v[160:163]
	v_mfma_f32_16x16x32_f16 v[156:159], v[116:119], v[136:139], v[156:159]
	v_mfma_f32_16x16x32_f16 v[124:127], v[96:99], v[148:151], v[124:127]
	v_mfma_f32_16x16x32_f16 v[120:123], v[116:119], v[148:151], v[120:123]
	v_mfma_f32_16x16x32_f16 v[100:103], v[96:99], v[164:167], v[100:103]
	v_mfma_f32_16x16x32_f16 v[92:95], v[116:119], v[164:167], v[92:95]
	v_mfma_f32_16x16x32_f16 v[76:79], v[96:99], v[172:175], v[76:79]
	v_mfma_f32_16x16x32_f16 v[72:75], v[116:119], v[172:175], v[72:75]
	s_barrier
	s_add_i32 s28, 0, 0x1c000
	s_add_i32 s29, s65, s44
	v_add_u32_e32 v188, s28, v241
	s_mov_b32 m0, s29
	ds_read_b128 v[176:179], v188
	ds_read_b128 v[180:183], v188 offset:1024
	ds_read_b128 v[184:187], v188 offset:2048
	ds_read_b128 v[188:191], v188 offset:3072
	global_load_lds_dwordx4 v206, s[72:73]
	s_add_i32 m0, s29, 0x2000
	s_nop 0
	global_load_lds_dwordx4 v210, s[72:73]
	s_barrier
	s_waitcnt lgkmcnt(0)
	v_mfma_f32_16x16x32_f16 v[140:143], v[176:179], v[132:135], v[140:143]
	v_mfma_f32_16x16x32_f16 v[128:131], v[184:187], v[132:135], v[128:131]
	v_mfma_f32_16x16x32_f16 v[112:115], v[176:179], v[144:147], v[112:115]
	v_mfma_f32_16x16x32_f16 v[104:107], v[184:187], v[144:147], v[104:107]
	v_mfma_f32_16x16x32_f16 v[84:87], v[176:179], v[152:155], v[84:87]
	v_mfma_f32_16x16x32_f16 v[80:83], v[184:187], v[152:155], v[80:83]
	v_mfma_f32_16x16x32_f16 v[68:71], v[176:179], v[168:171], v[68:71]
	v_mfma_f32_16x16x32_f16 v[64:67], v[184:187], v[168:171], v[64:67]
	v_mfma_f32_16x16x32_f16 v[140:143], v[180:183], v[136:139], v[140:143]
	v_mfma_f32_16x16x32_f16 v[132:135], v[188:191], v[136:139], v[128:131]
	v_mfma_f32_16x16x32_f16 v[112:115], v[180:183], v[148:151], v[112:115]
	v_mfma_f32_16x16x32_f16 v[104:107], v[188:191], v[148:151], v[104:107]
	v_mfma_f32_16x16x32_f16 v[84:87], v[180:183], v[164:167], v[84:87]
	v_mfma_f32_16x16x32_f16 v[80:83], v[188:191], v[164:167], v[80:83]
	v_mfma_f32_16x16x32_f16 v[68:71], v[180:183], v[172:175], v[68:71]
	v_mfma_f32_16x16x32_f16 v[64:67], v[188:191], v[172:175], v[64:67]
	s_barrier
	s_mov_b32 m0, s51
	ds_read_b128 v[128:131], v244 offset:49152
	ds_read_b128 v[136:139], v244 offset:50176
	ds_read_b128 v[144:147], v244 offset:51200
	ds_read_b128 v[148:151], v244 offset:52224
	ds_read_b128 v[152:155], v244 offset:53248
	ds_read_b128 v[164:167], v244 offset:54272
	ds_read_b128 v[168:171], v244 offset:55296
	ds_read_b128 v[172:175], v244 offset:56320
	global_load_lds_dwordx4 v204, s[74:75]
	s_mov_b32 m0, s54
	s_nop 0
	global_load_lds_dwordx4 v208, s[74:75]
	s_barrier
	s_waitcnt lgkmcnt(0)
	v_mfma_f32_16x16x32_f16 v[60:63], v[88:91], v[128:131], v[60:63]
	v_mfma_f32_16x16x32_f16 v[56:59], v[108:111], v[128:131], v[56:59]
	v_mfma_f32_16x16x32_f16 v[44:47], v[88:91], v[144:147], v[44:47]
	v_mfma_f32_16x16x32_f16 v[40:43], v[108:111], v[144:147], v[40:43]
	v_mfma_f32_16x16x32_f16 v[28:31], v[88:91], v[152:155], v[28:31]
	v_mfma_f32_16x16x32_f16 v[24:27], v[108:111], v[152:155], v[24:27]
	v_mfma_f32_16x16x32_f16 v[12:15], v[88:91], v[168:171], v[12:15]
	v_mfma_f32_16x16x32_f16 v[8:11], v[108:111], v[168:171], v[8:11]
	v_mfma_f32_16x16x32_f16 v[60:63], v[96:99], v[136:139], v[60:63]
	v_mfma_f32_16x16x32_f16 v[56:59], v[116:119], v[136:139], v[56:59]
	v_mfma_f32_16x16x32_f16 v[44:47], v[96:99], v[148:151], v[44:47]
	v_mfma_f32_16x16x32_f16 v[40:43], v[116:119], v[148:151], v[40:43]
	v_mfma_f32_16x16x32_f16 v[28:31], v[96:99], v[164:167], v[28:31]
	v_mfma_f32_16x16x32_f16 v[24:27], v[116:119], v[164:167], v[24:27]
	v_mfma_f32_16x16x32_f16 v[12:15], v[96:99], v[172:175], v[12:15]
	v_mfma_f32_16x16x32_f16 v[8:11], v[116:119], v[172:175], v[8:11]
	s_barrier
	s_add_u32 s26, s26, 0x80080
	s_addc_u32 s27, s27, 0
	s_add_i32 s28, s28, s44
	s_mov_b32 m0, s28
	s_nop 0
	global_load_lds_dwordx4 v206, s[26:27]
	s_add_i32 m0, s28, 0x2000
	s_nop 0
	global_load_lds_dwordx4 v210, s[26:27]
	s_waitcnt vmcnt(6)
	s_barrier
	v_mfma_f32_16x16x32_f16 v[52:55], v[176:179], v[128:131], v[52:55]
	v_mfma_f32_16x16x32_f16 v[48:51], v[184:187], v[128:131], v[48:51]
	v_mfma_f32_16x16x32_f16 v[36:39], v[176:179], v[144:147], v[36:39]
	v_mfma_f32_16x16x32_f16 v[32:35], v[184:187], v[144:147], v[32:35]
	v_mfma_f32_16x16x32_f16 v[20:23], v[176:179], v[152:155], v[20:23]
	v_mfma_f32_16x16x32_f16 v[16:19], v[184:187], v[152:155], v[16:19]
	v_mfma_f32_16x16x32_f16 v[4:7], v[176:179], v[168:171], v[4:7]
	v_mfma_f32_16x16x32_f16 v[0:3], v[184:187], v[168:171], v[0:3]
	v_mfma_f32_16x16x32_f16 v[52:55], v[180:183], v[136:139], v[52:55]
	v_mfma_f32_16x16x32_f16 v[48:51], v[188:191], v[136:139], v[48:51]
	v_mfma_f32_16x16x32_f16 v[36:39], v[180:183], v[148:151], v[36:39]
	v_mfma_f32_16x16x32_f16 v[32:35], v[188:191], v[148:151], v[32:35]
	v_mfma_f32_16x16x32_f16 v[20:23], v[180:183], v[164:167], v[20:23]
	v_mfma_f32_16x16x32_f16 v[16:19], v[188:191], v[164:167], v[16:19]
	v_mfma_f32_16x16x32_f16 v[4:7], v[180:183], v[172:175], v[4:7]
	v_mfma_f32_16x16x32_f16 v[0:3], v[188:191], v[172:175], v[0:3]
	s_barrier
	s_add_i32 s64, s64, 2
	s_add_u32 s24, s24, 0x100
	s_addc_u32 s25, s25, 0
	s_add_u32 s62, s62, 0x100
	s_addc_u32 s63, s63, 0
	s_cmp_gt_u32 s64, 29
	s_cbranch_scc0 .LBB0_1185
	s_setprio 0
	s_lshl_b32 s15, s22, 8
	s_add_i32 s17, s15, 0xffffe000
	s_lshr_b32 s17, s17, 11
	s_mulk_i32 s17, 0x1800
	s_addk_i32 s17, 0x1800
	s_cmp_gt_i32 s22, 31
	s_cselect_b32 s24, s17, 0
	s_ashr_i32 s25, s24, 31
	v_lshl_or_b32 v128, s30, 8, v242
	s_lshl_b64 s[24:25], s[24:25], 2
	s_add_u32 s24, s42, s24
	v_ashrrev_i32_e32 v129, 31, v128
	v_add_u32_e32 v130, s15, v240
	s_addc_u32 s25, s43, s25
	v_lshlrev_b64 v[220:221], 1, v[128:129]
	v_ashrrev_i32_e32 v131, 31, v130
	v_lshl_add_u64 v[96:97], v[128:129], 2, s[24:25]
	v_lshl_add_u64 v[128:129], s[4:5], 0, v[220:221]
	v_lshlrev_b64 v[236:237], 12, v[130:131]
	v_lshl_add_u64 v[136:137], v[128:129], 0, v[236:237]
	global_load_dwordx4 v[108:111], v[96:97], off offset:16
	global_load_dwordx4 v[116:119], v[96:97], off
	global_load_dwordx4 v[88:91], v[96:97], off offset:528
	s_nop 0
	global_load_dwordx4 v[96:99], v[96:97], off offset:512
	s_nop 0
	global_load_dwordx4 v[246:249], v[136:137], off nt
	global_load_dwordx4 v[200:203], v[136:137], off offset:256 nt
	v_or_b32_e32 v136, 16, v130
	v_ashrrev_i32_e32 v137, 31, v136
	v_lshlrev_b64 v[234:235], 12, v[136:137]
	v_lshl_add_u64 v[136:137], v[128:129], 0, v[234:235]
	global_load_dwordx4 v[196:199], v[136:137], off nt
	global_load_dwordx4 v[192:195], v[136:137], off offset:256 nt
	v_or_b32_e32 v136, 32, v130
	v_ashrrev_i32_e32 v137, 31, v136
	v_lshlrev_b64 v[232:233], 12, v[136:137]
	v_lshl_add_u64 v[136:137], v[128:129], 0, v[232:233]
	global_load_dwordx4 v[188:191], v[136:137], off nt
	global_load_dwordx4 v[184:187], v[136:137], off offset:256 nt
	v_readlane_b32 s64, v254, 21
	v_readlane_b32 s68, v254, 25
	v_readlane_b32 s69, v254, 26
	s_mov_b64 s[56:57], s[68:69]
	v_or_b32_e32 v130, 48, v130
	v_ashrrev_i32_e32 v131, 31, v130
	v_lshlrev_b64 v[230:231], 12, v[130:131]
	v_lshl_add_u64 v[130:131], v[128:129], 0, v[230:231]
	global_load_dwordx4 v[180:183], v[130:131], off nt
	global_load_dwordx4 v[176:179], v[130:131], off offset:256 nt
	v_lshl_add_u64 v[228:229], v[236:237], 0, s[0:1]
	v_lshl_add_u64 v[130:131], v[128:129], 0, v[228:229]
	global_load_dwordx4 v[172:175], v[130:131], off nt
	global_load_dwordx4 v[168:171], v[130:131], off offset:256 nt
	v_lshl_add_u64 v[226:227], v[236:237], 0, s[8:9]
	v_lshl_add_u64 v[130:131], v[128:129], 0, v[226:227]
	global_load_dwordx4 v[164:167], v[130:131], off nt
	global_load_dwordx4 v[152:155], v[130:131], off offset:256 nt
	v_lshl_add_u64 v[224:225], v[236:237], 0, s[10:11]
	v_lshl_add_u64 v[130:131], v[128:129], 0, v[224:225]
	global_load_dwordx4 v[148:151], v[130:131], off nt
	global_load_dwordx4 v[144:147], v[130:131], off offset:256 nt
	v_lshl_add_u64 v[222:223], v[236:237], 0, s[12:13]
	v_lshl_add_u64 v[128:129], v[128:129], 0, v[222:223]
	global_load_dwordx4 v[136:139], v[128:129], off nt
	s_nop 0
	global_load_dwordx4 v[128:131], v[128:129], off offset:256 nt
	s_and_b64 vcc, exec, s[2:3]
	s_mov_b32 s30, s14
	s_mov_b32 s22, s16
	s_mov_b64 s[26:27], s[20:21]
	s_mov_b64 s[24:25], s[18:19]
	v_readlane_b32 s65, v254, 22
	v_readlane_b32 s66, v254, 23
	v_readlane_b32 s67, v254, 24
	v_readlane_b32 s70, v254, 27
	v_readlane_b32 s71, v254, 28
	v_readlane_b32 s72, v254, 29
	v_readlane_b32 s73, v254, 30
	v_readlane_b32 s74, v254, 31
	v_readlane_b32 s75, v254, 32
	v_readlane_b32 s76, v254, 33
	v_readlane_b32 s77, v254, 34
	v_readlane_b32 s78, v254, 35
	v_readlane_b32 s79, v254, 36
	s_waitcnt vmcnt(0)
	v_cvt_f32_f16_e32 v250, v246
	v_cvt_f32_f16_sdwa v251, v246 dst_sel:DWORD dst_unused:UNUSED_PAD src0_sel:WORD_1
	v_pk_fma_f32 v[160:161], v[160:161], v[116:117], v[250:251]
	s_nop 0
	v_cvt_pk_f16_f32 v246, v160, v161
	v_cvt_f32_f16_e32 v160, v248
	v_cvt_f32_f16_sdwa v161, v248 dst_sel:DWORD dst_unused:UNUSED_PAD src0_sel:WORD_1
	v_pk_fma_f32 v[156:157], v[156:157], v[108:109], v[160:161]
	s_nop 0
	v_cvt_pk_f16_f32 v248, v156, v157
	v_cvt_f32_f16_e32 v156, v247
	v_cvt_f32_f16_sdwa v157, v247 dst_sel:DWORD dst_unused:UNUSED_PAD src0_sel:WORD_1
	v_pk_fma_f32 v[156:157], v[162:163], v[118:119], v[156:157]
	s_nop 0
	v_cvt_pk_f16_f32 v247, v156, v157
	v_cvt_f32_f16_e32 v156, v249
	v_cvt_f32_f16_sdwa v157, v249 dst_sel:DWORD dst_unused:UNUSED_PAD src0_sel:WORD_1
	v_pk_fma_f32 v[156:157], v[158:159], v[110:111], v[156:157]
	s_nop 0
	v_cvt_pk_f16_f32 v249, v156, v157
	v_lshl_add_u64 v[156:157], s[56:57], 0, v[236:237]
	v_lshl_add_u64 v[160:161], v[156:157], 0, v[220:221]
	v_cvt_f32_f16_e32 v156, v200
	v_cvt_f32_f16_sdwa v157, v200 dst_sel:DWORD dst_unused:UNUSED_PAD src0_sel:WORD_1
	global_store_dwordx4 v[160:161], v[246:249], off
	v_pk_fma_f32 v[140:141], v[140:141], v[96:97], v[156:157]
	s_nop 0
	v_cvt_pk_f16_f32 v156, v140, v141
	v_cvt_f32_f16_e32 v140, v202
	v_cvt_f32_f16_sdwa v141, v202 dst_sel:DWORD dst_unused:UNUSED_PAD src0_sel:WORD_1
	v_pk_fma_f32 v[132:133], v[132:133], v[88:89], v[140:141]
	s_nop 0
	v_cvt_pk_f16_f32 v158, v132, v133
	v_cvt_f32_f16_e32 v132, v201
	v_cvt_f32_f16_sdwa v133, v201 dst_sel:DWORD dst_unused:UNUSED_PAD src0_sel:WORD_1
	v_pk_fma_f32 v[132:133], v[142:143], v[98:99], v[132:133]
	s_nop 0
	v_cvt_pk_f16_f32 v157, v132, v133
	v_cvt_f32_f16_e32 v132, v203
	v_cvt_f32_f16_sdwa v133, v203 dst_sel:DWORD dst_unused:UNUSED_PAD src0_sel:WORD_1
	v_pk_fma_f32 v[132:133], v[134:135], v[90:91], v[132:133]
	s_nop 0
	v_cvt_pk_f16_f32 v159, v132, v133
	v_cvt_f32_f16_e32 v132, v196
	v_cvt_f32_f16_sdwa v133, v196 dst_sel:DWORD dst_unused:UNUSED_PAD src0_sel:WORD_1
	global_store_dwordx4 v[160:161], v[156:159], off offset:256
	v_pk_fma_f32 v[124:125], v[124:125], v[116:117], v[132:133]
	s_nop 0
	v_cvt_pk_f16_f32 v132, v124, v125
	v_cvt_f32_f16_e32 v124, v198
	v_cvt_f32_f16_sdwa v125, v198 dst_sel:DWORD dst_unused:UNUSED_PAD src0_sel:WORD_1
	v_pk_fma_f32 v[120:121], v[120:121], v[108:109], v[124:125]
	s_nop 0
	v_cvt_pk_f16_f32 v134, v120, v121
	v_cvt_f32_f16_e32 v120, v197
	v_cvt_f32_f16_sdwa v121, v197 dst_sel:DWORD dst_unused:UNUSED_PAD src0_sel:WORD_1
	v_pk_fma_f32 v[120:121], v[126:127], v[118:119], v[120:121]
	s_nop 0
	v_cvt_pk_f16_f32 v133, v120, v121
	v_cvt_f32_f16_e32 v120, v199
	v_cvt_f32_f16_sdwa v121, v199 dst_sel:DWORD dst_unused:UNUSED_PAD src0_sel:WORD_1
	v_pk_fma_f32 v[120:121], v[122:123], v[110:111], v[120:121]
	s_nop 0
	v_cvt_pk_f16_f32 v135, v120, v121
	v_lshl_add_u64 v[120:121], s[56:57], 0, v[234:235]
	v_lshl_add_u64 v[124:125], v[120:121], 0, v[220:221]
	v_cvt_f32_f16_e32 v120, v192
	v_cvt_f32_f16_sdwa v121, v192 dst_sel:DWORD dst_unused:UNUSED_PAD src0_sel:WORD_1
	global_store_dwordx4 v[124:125], v[132:135], off
	v_pk_fma_f32 v[112:113], v[112:113], v[96:97], v[120:121]
	s_nop 0
	v_cvt_pk_f16_f32 v120, v112, v113
	v_cvt_f32_f16_e32 v112, v194
	v_cvt_f32_f16_sdwa v113, v194 dst_sel:DWORD dst_unused:UNUSED_PAD src0_sel:WORD_1
	v_pk_fma_f32 v[104:105], v[104:105], v[88:89], v[112:113]
	s_nop 0
	v_cvt_pk_f16_f32 v122, v104, v105
	v_cvt_f32_f16_e32 v104, v193
	v_cvt_f32_f16_sdwa v105, v193 dst_sel:DWORD dst_unused:UNUSED_PAD src0_sel:WORD_1
	v_pk_fma_f32 v[104:105], v[114:115], v[98:99], v[104:105]
	s_nop 0
	v_cvt_pk_f16_f32 v121, v104, v105
	v_cvt_f32_f16_e32 v104, v195
	v_cvt_f32_f16_sdwa v105, v195 dst_sel:DWORD dst_unused:UNUSED_PAD src0_sel:WORD_1
	v_pk_fma_f32 v[104:105], v[106:107], v[90:91], v[104:105]
	s_nop 0
	v_cvt_pk_f16_f32 v123, v104, v105
	v_cvt_f32_f16_e32 v104, v188
	v_cvt_f32_f16_sdwa v105, v188 dst_sel:DWORD dst_unused:UNUSED_PAD src0_sel:WORD_1
	global_store_dwordx4 v[124:125], v[120:123], off offset:256
	v_pk_fma_f32 v[100:101], v[100:101], v[116:117], v[104:105]
	s_nop 0
	v_cvt_pk_f16_f32 v104, v100, v101
	v_cvt_f32_f16_e32 v100, v190
	v_cvt_f32_f16_sdwa v101, v190 dst_sel:DWORD dst_unused:UNUSED_PAD src0_sel:WORD_1
	v_pk_fma_f32 v[92:93], v[92:93], v[108:109], v[100:101]
	s_nop 0
	v_cvt_pk_f16_f32 v106, v92, v93
	v_cvt_f32_f16_e32 v92, v189
	v_cvt_f32_f16_sdwa v93, v189 dst_sel:DWORD dst_unused:UNUSED_PAD src0_sel:WORD_1
	v_pk_fma_f32 v[92:93], v[102:103], v[118:119], v[92:93]
	s_nop 0
	v_cvt_pk_f16_f32 v105, v92, v93
	v_cvt_f32_f16_e32 v92, v191
	v_cvt_f32_f16_sdwa v93, v191 dst_sel:DWORD dst_unused:UNUSED_PAD src0_sel:WORD_1
	v_pk_fma_f32 v[92:93], v[94:95], v[110:111], v[92:93]
	s_nop 0
	v_cvt_pk_f16_f32 v107, v92, v93
	v_lshl_add_u64 v[92:93], s[56:57], 0, v[232:233]
	v_lshl_add_u64 v[100:101], v[92:93], 0, v[220:221]
	v_cvt_f32_f16_e32 v92, v184
	v_cvt_f32_f16_sdwa v93, v184 dst_sel:DWORD dst_unused:UNUSED_PAD src0_sel:WORD_1
	global_store_dwordx4 v[100:101], v[104:107], off
	v_pk_fma_f32 v[84:85], v[84:85], v[96:97], v[92:93]
	s_nop 0
	v_cvt_pk_f16_f32 v92, v84, v85
	v_cvt_f32_f16_e32 v84, v186
	v_cvt_f32_f16_sdwa v85, v186 dst_sel:DWORD dst_unused:UNUSED_PAD src0_sel:WORD_1
	v_pk_fma_f32 v[80:81], v[80:81], v[88:89], v[84:85]
	s_nop 0
	v_cvt_pk_f16_f32 v94, v80, v81
	v_cvt_f32_f16_e32 v80, v185
	v_cvt_f32_f16_sdwa v81, v185 dst_sel:DWORD dst_unused:UNUSED_PAD src0_sel:WORD_1
	v_pk_fma_f32 v[80:81], v[86:87], v[98:99], v[80:81]
	s_nop 0
	v_cvt_pk_f16_f32 v93, v80, v81
	v_cvt_f32_f16_e32 v80, v187
	v_cvt_f32_f16_sdwa v81, v187 dst_sel:DWORD dst_unused:UNUSED_PAD src0_sel:WORD_1
	v_pk_fma_f32 v[80:81], v[82:83], v[90:91], v[80:81]
	s_nop 0
	v_cvt_pk_f16_f32 v95, v80, v81
	v_cvt_f32_f16_e32 v80, v180
	v_cvt_f32_f16_sdwa v81, v180 dst_sel:DWORD dst_unused:UNUSED_PAD src0_sel:WORD_1
	global_store_dwordx4 v[100:101], v[92:95], off offset:256
	v_pk_fma_f32 v[76:77], v[76:77], v[116:117], v[80:81]
	s_nop 0
	v_cvt_pk_f16_f32 v80, v76, v77
	v_cvt_f32_f16_e32 v76, v182
	v_cvt_f32_f16_sdwa v77, v182 dst_sel:DWORD dst_unused:UNUSED_PAD src0_sel:WORD_1
	v_pk_fma_f32 v[72:73], v[72:73], v[108:109], v[76:77]
	s_nop 0
	v_cvt_pk_f16_f32 v82, v72, v73
	v_cvt_f32_f16_e32 v72, v181
	v_cvt_f32_f16_sdwa v73, v181 dst_sel:DWORD dst_unused:UNUSED_PAD src0_sel:WORD_1
	v_pk_fma_f32 v[72:73], v[78:79], v[118:119], v[72:73]
	s_nop 0
	v_cvt_pk_f16_f32 v81, v72, v73
	v_cvt_f32_f16_e32 v72, v183
	v_cvt_f32_f16_sdwa v73, v183 dst_sel:DWORD dst_unused:UNUSED_PAD src0_sel:WORD_1
	v_pk_fma_f32 v[72:73], v[74:75], v[110:111], v[72:73]
	s_nop 0
	v_cvt_pk_f16_f32 v83, v72, v73
	v_lshl_add_u64 v[72:73], s[56:57], 0, v[230:231]
	v_lshl_add_u64 v[76:77], v[72:73], 0, v[220:221]
	v_cvt_f32_f16_e32 v72, v176
	v_cvt_f32_f16_sdwa v73, v176 dst_sel:DWORD dst_unused:UNUSED_PAD src0_sel:WORD_1
	global_store_dwordx4 v[76:77], v[80:83], off
	v_pk_fma_f32 v[68:69], v[68:69], v[96:97], v[72:73]
	s_nop 0
	v_cvt_pk_f16_f32 v72, v68, v69
	v_cvt_f32_f16_e32 v68, v178
	v_cvt_f32_f16_sdwa v69, v178 dst_sel:DWORD dst_unused:UNUSED_PAD src0_sel:WORD_1
	v_pk_fma_f32 v[64:65], v[64:65], v[88:89], v[68:69]
	s_nop 0
	v_cvt_pk_f16_f32 v74, v64, v65
	v_cvt_f32_f16_e32 v64, v177
	v_cvt_f32_f16_sdwa v65, v177 dst_sel:DWORD dst_unused:UNUSED_PAD src0_sel:WORD_1
	v_pk_fma_f32 v[64:65], v[70:71], v[98:99], v[64:65]
	s_nop 0
	v_cvt_pk_f16_f32 v73, v64, v65
	v_cvt_f32_f16_e32 v64, v179
	v_cvt_f32_f16_sdwa v65, v179 dst_sel:DWORD dst_unused:UNUSED_PAD src0_sel:WORD_1
	v_pk_fma_f32 v[64:65], v[66:67], v[90:91], v[64:65]
	s_nop 0
	v_cvt_pk_f16_f32 v75, v64, v65
	v_cvt_f32_f16_e32 v64, v172
	v_cvt_f32_f16_sdwa v65, v172 dst_sel:DWORD dst_unused:UNUSED_PAD src0_sel:WORD_1
	global_store_dwordx4 v[76:77], v[72:75], off offset:256
	v_pk_fma_f32 v[60:61], v[60:61], v[116:117], v[64:65]
	s_nop 0
	v_cvt_pk_f16_f32 v64, v60, v61
	v_cvt_f32_f16_e32 v60, v174
	v_cvt_f32_f16_sdwa v61, v174 dst_sel:DWORD dst_unused:UNUSED_PAD src0_sel:WORD_1
	v_pk_fma_f32 v[56:57], v[56:57], v[108:109], v[60:61]
	s_nop 0
	v_cvt_pk_f16_f32 v66, v56, v57
	v_cvt_f32_f16_e32 v56, v173
	v_cvt_f32_f16_sdwa v57, v173 dst_sel:DWORD dst_unused:UNUSED_PAD src0_sel:WORD_1
	v_pk_fma_f32 v[56:57], v[62:63], v[118:119], v[56:57]
	s_nop 0
	v_cvt_pk_f16_f32 v65, v56, v57
	v_cvt_f32_f16_e32 v56, v175
	v_cvt_f32_f16_sdwa v57, v175 dst_sel:DWORD dst_unused:UNUSED_PAD src0_sel:WORD_1
	v_pk_fma_f32 v[56:57], v[58:59], v[110:111], v[56:57]
	s_nop 0
	v_cvt_pk_f16_f32 v67, v56, v57
	v_lshl_add_u64 v[56:57], s[56:57], 0, v[228:229]
	v_lshl_add_u64 v[60:61], v[56:57], 0, v[220:221]
	v_cvt_f32_f16_e32 v56, v168
	v_cvt_f32_f16_sdwa v57, v168 dst_sel:DWORD dst_unused:UNUSED_PAD src0_sel:WORD_1
	global_store_dwordx4 v[60:61], v[64:67], off
	v_pk_fma_f32 v[52:53], v[52:53], v[96:97], v[56:57]
	s_nop 0
	v_cvt_pk_f16_f32 v56, v52, v53
	v_cvt_f32_f16_e32 v52, v170
	v_cvt_f32_f16_sdwa v53, v170 dst_sel:DWORD dst_unused:UNUSED_PAD src0_sel:WORD_1
	v_pk_fma_f32 v[48:49], v[48:49], v[88:89], v[52:53]
	s_nop 0
	v_cvt_pk_f16_f32 v58, v48, v49
	v_cvt_f32_f16_e32 v48, v169
	v_cvt_f32_f16_sdwa v49, v169 dst_sel:DWORD dst_unused:UNUSED_PAD src0_sel:WORD_1
	v_pk_fma_f32 v[48:49], v[54:55], v[98:99], v[48:49]
	s_nop 0
	v_cvt_pk_f16_f32 v57, v48, v49
	v_cvt_f32_f16_e32 v48, v171
	v_cvt_f32_f16_sdwa v49, v171 dst_sel:DWORD dst_unused:UNUSED_PAD src0_sel:WORD_1
	v_pk_fma_f32 v[48:49], v[50:51], v[90:91], v[48:49]
	s_nop 0
	v_cvt_pk_f16_f32 v59, v48, v49
	v_cvt_f32_f16_e32 v48, v164
	v_cvt_f32_f16_sdwa v49, v164 dst_sel:DWORD dst_unused:UNUSED_PAD src0_sel:WORD_1
	global_store_dwordx4 v[60:61], v[56:59], off offset:256
	v_pk_fma_f32 v[44:45], v[44:45], v[116:117], v[48:49]
	s_nop 0
	v_cvt_pk_f16_f32 v48, v44, v45
	v_cvt_f32_f16_e32 v44, v166
	v_cvt_f32_f16_sdwa v45, v166 dst_sel:DWORD dst_unused:UNUSED_PAD src0_sel:WORD_1
	v_pk_fma_f32 v[40:41], v[40:41], v[108:109], v[44:45]
	s_nop 0
	v_cvt_pk_f16_f32 v50, v40, v41
	v_cvt_f32_f16_e32 v40, v165
	v_cvt_f32_f16_sdwa v41, v165 dst_sel:DWORD dst_unused:UNUSED_PAD src0_sel:WORD_1
	v_pk_fma_f32 v[40:41], v[46:47], v[118:119], v[40:41]
	s_nop 0
	v_cvt_pk_f16_f32 v49, v40, v41
	v_cvt_f32_f16_e32 v40, v167
	v_cvt_f32_f16_sdwa v41, v167 dst_sel:DWORD dst_unused:UNUSED_PAD src0_sel:WORD_1
	v_pk_fma_f32 v[40:41], v[42:43], v[110:111], v[40:41]
	s_nop 0
	v_cvt_pk_f16_f32 v51, v40, v41
	v_lshl_add_u64 v[40:41], s[56:57], 0, v[226:227]
	v_lshl_add_u64 v[44:45], v[40:41], 0, v[220:221]
	v_cvt_f32_f16_e32 v40, v152
	v_cvt_f32_f16_sdwa v41, v152 dst_sel:DWORD dst_unused:UNUSED_PAD src0_sel:WORD_1
	global_store_dwordx4 v[44:45], v[48:51], off
	v_pk_fma_f32 v[36:37], v[36:37], v[96:97], v[40:41]
	s_nop 0
	v_cvt_pk_f16_f32 v40, v36, v37
	v_cvt_f32_f16_e32 v36, v154
	v_cvt_f32_f16_sdwa v37, v154 dst_sel:DWORD dst_unused:UNUSED_PAD src0_sel:WORD_1
	v_pk_fma_f32 v[32:33], v[32:33], v[88:89], v[36:37]
	s_nop 0
	v_cvt_pk_f16_f32 v42, v32, v33
	v_cvt_f32_f16_e32 v32, v153
	v_cvt_f32_f16_sdwa v33, v153 dst_sel:DWORD dst_unused:UNUSED_PAD src0_sel:WORD_1
	v_pk_fma_f32 v[32:33], v[38:39], v[98:99], v[32:33]
	s_nop 0
	v_cvt_pk_f16_f32 v41, v32, v33
	v_cvt_f32_f16_e32 v32, v155
	v_cvt_f32_f16_sdwa v33, v155 dst_sel:DWORD dst_unused:UNUSED_PAD src0_sel:WORD_1
	v_pk_fma_f32 v[32:33], v[34:35], v[90:91], v[32:33]
	s_nop 0
	v_cvt_pk_f16_f32 v43, v32, v33
	v_cvt_f32_f16_e32 v32, v148
	v_cvt_f32_f16_sdwa v33, v148 dst_sel:DWORD dst_unused:UNUSED_PAD src0_sel:WORD_1
	global_store_dwordx4 v[44:45], v[40:43], off offset:256
	v_pk_fma_f32 v[28:29], v[28:29], v[116:117], v[32:33]
	s_nop 0
	v_cvt_pk_f16_f32 v32, v28, v29
	v_cvt_f32_f16_e32 v28, v150
	v_cvt_f32_f16_sdwa v29, v150 dst_sel:DWORD dst_unused:UNUSED_PAD src0_sel:WORD_1
	v_pk_fma_f32 v[24:25], v[24:25], v[108:109], v[28:29]
	s_nop 0
	v_cvt_pk_f16_f32 v34, v24, v25
	v_cvt_f32_f16_e32 v24, v149
	v_cvt_f32_f16_sdwa v25, v149 dst_sel:DWORD dst_unused:UNUSED_PAD src0_sel:WORD_1
	v_pk_fma_f32 v[24:25], v[30:31], v[118:119], v[24:25]
	s_nop 0
	v_cvt_pk_f16_f32 v33, v24, v25
	v_cvt_f32_f16_e32 v24, v151
	v_cvt_f32_f16_sdwa v25, v151 dst_sel:DWORD dst_unused:UNUSED_PAD src0_sel:WORD_1
	v_pk_fma_f32 v[24:25], v[26:27], v[110:111], v[24:25]
	s_nop 0
	v_cvt_pk_f16_f32 v35, v24, v25
	v_lshl_add_u64 v[24:25], s[56:57], 0, v[224:225]
	v_lshl_add_u64 v[28:29], v[24:25], 0, v[220:221]
	v_cvt_f32_f16_e32 v24, v144
	v_cvt_f32_f16_sdwa v25, v144 dst_sel:DWORD dst_unused:UNUSED_PAD src0_sel:WORD_1
	global_store_dwordx4 v[28:29], v[32:35], off
	v_pk_fma_f32 v[20:21], v[20:21], v[96:97], v[24:25]
	s_nop 0
	v_cvt_pk_f16_f32 v24, v20, v21
	v_cvt_f32_f16_e32 v20, v146
	v_cvt_f32_f16_sdwa v21, v146 dst_sel:DWORD dst_unused:UNUSED_PAD src0_sel:WORD_1
	v_pk_fma_f32 v[16:17], v[16:17], v[88:89], v[20:21]
	s_nop 0
	v_cvt_pk_f16_f32 v26, v16, v17
	v_cvt_f32_f16_e32 v16, v145
	v_cvt_f32_f16_sdwa v17, v145 dst_sel:DWORD dst_unused:UNUSED_PAD src0_sel:WORD_1
	v_pk_fma_f32 v[16:17], v[22:23], v[98:99], v[16:17]
	s_nop 0
	v_cvt_pk_f16_f32 v25, v16, v17
	v_cvt_f32_f16_e32 v16, v147
	v_cvt_f32_f16_sdwa v17, v147 dst_sel:DWORD dst_unused:UNUSED_PAD src0_sel:WORD_1
	v_pk_fma_f32 v[16:17], v[18:19], v[90:91], v[16:17]
	s_nop 0
	v_cvt_pk_f16_f32 v27, v16, v17
	v_cvt_f32_f16_e32 v16, v136
	v_cvt_f32_f16_sdwa v17, v136 dst_sel:DWORD dst_unused:UNUSED_PAD src0_sel:WORD_1
	global_store_dwordx4 v[28:29], v[24:27], off offset:256
	v_pk_fma_f32 v[12:13], v[12:13], v[116:117], v[16:17]
	s_nop 0
	v_cvt_pk_f16_f32 v16, v12, v13
	v_cvt_f32_f16_e32 v12, v138
	v_cvt_f32_f16_sdwa v13, v138 dst_sel:DWORD dst_unused:UNUSED_PAD src0_sel:WORD_1
	v_pk_fma_f32 v[8:9], v[8:9], v[108:109], v[12:13]
	s_nop 0
	v_cvt_pk_f16_f32 v18, v8, v9
	v_cvt_f32_f16_e32 v8, v137
	v_cvt_f32_f16_sdwa v9, v137 dst_sel:DWORD dst_unused:UNUSED_PAD src0_sel:WORD_1
	v_pk_fma_f32 v[8:9], v[14:15], v[118:119], v[8:9]
	s_nop 0
	v_cvt_pk_f16_f32 v17, v8, v9
	v_cvt_f32_f16_e32 v8, v139
	v_cvt_f32_f16_sdwa v9, v139 dst_sel:DWORD dst_unused:UNUSED_PAD src0_sel:WORD_1
	v_pk_fma_f32 v[8:9], v[10:11], v[110:111], v[8:9]
	s_nop 0
	v_cvt_pk_f16_f32 v19, v8, v9
	v_lshl_add_u64 v[8:9], s[56:57], 0, v[222:223]
	v_lshl_add_u64 v[12:13], v[8:9], 0, v[220:221]
	v_cvt_f32_f16_e32 v8, v128
	v_cvt_f32_f16_sdwa v9, v128 dst_sel:DWORD dst_unused:UNUSED_PAD src0_sel:WORD_1
	global_store_dwordx4 v[12:13], v[16:19], off
	v_pk_fma_f32 v[4:5], v[4:5], v[96:97], v[8:9]
	s_nop 0
	v_cvt_pk_f16_f32 v8, v4, v5
	v_cvt_f32_f16_e32 v4, v130
	v_cvt_f32_f16_sdwa v5, v130 dst_sel:DWORD dst_unused:UNUSED_PAD src0_sel:WORD_1
	v_pk_fma_f32 v[0:1], v[0:1], v[88:89], v[4:5]
	s_nop 0
	v_cvt_pk_f16_f32 v10, v0, v1
	v_cvt_f32_f16_e32 v0, v129
	v_cvt_f32_f16_sdwa v1, v129 dst_sel:DWORD dst_unused:UNUSED_PAD src0_sel:WORD_1
	v_pk_fma_f32 v[0:1], v[6:7], v[98:99], v[0:1]
	s_nop 0
	v_cvt_pk_f16_f32 v9, v0, v1
	v_cvt_f32_f16_e32 v0, v131
	v_cvt_f32_f16_sdwa v1, v131 dst_sel:DWORD dst_unused:UNUSED_PAD src0_sel:WORD_1
	v_pk_fma_f32 v[0:1], v[2:3], v[90:91], v[0:1]
	s_nop 0
	v_cvt_pk_f16_f32 v11, v0, v1
	global_store_dwordx4 v[12:13], v[8:11], off offset:256
	s_cbranch_vccz .LBB0_1178
	s_waitcnt vmcnt(0)
	s_cmpk_gt_u32 s34, 0xff
	s_cbranch_scc1 .LBB0_1189
	s_barrier
